# conv part 2: third round of items spread over all workgroups instead of the first half of the grid
# speedup vs baseline: 1.0052x; 1.0052x over previous
; __device__ __forceinline__ void conv_phase(KP kp, int l, int a0t, int na) {
;     ...
;     for (int idx = blockIdx.x * 512 + tid_; idx < total; idx += NT) {
;         const int chunk = idx % nchunk, row0 = (idx / nchunk) * 8, t0 = row0 & (SEQ - 1), ca = chunk * 8, j = a0t * 256 + ca;
;         float wa[3][8], wb[3][8], ba[8], bb[8];
; #pragma unroll
;         for (int k = 0; k < 3; ++k) { const float* wk = cw + (size_t)k * NUP + j; const f32x4 a0 = *(const f32x4*)wk, a1 = *(const f32x4*)(wk + 4), b0 = *(const f32x4*)(wk + FF), b1 = *(const f32x4*)(wk + FF + 4);
; #pragma unroll
;             for (int e = 0; e < 4; ++e) { wa[k][e] = a0[e]; wa[k][4 + e] = a1[e]; wb[k][e] = b0[e]; wb[k][4 + e] = b1[e]; } }
;         { const f32x4 a0 = *(const f32x4*)(cb + j), a1 = *(const f32x4*)(cb + j + 4), b0 = *(const f32x4*)(cb + FF + j), b1 = *(const f32x4*)(cb + FF + j + 4);
; #pragma unroll
;           for (int e = 0; e < 4; ++e) { ba[e] = a0[e]; ba[4 + e] = a1[e]; bb[e] = b0[e]; bb[4 + e] = b1[e]; } }
;         const bf16_t* src = UPP + (size_t)row0 * ldu + ca;
;         u32x4 ra[10], rb[10];
; #pragma unroll
;         for (int i = 0; i < 10; ++i) { if (i >= 2 || t0 > 0) { ra[i] = *(const u32x4*)(src + (ptrdiff_t)(i - 2) * ldu); rb[i] = *(const u32x4*)(src + (ptrdiff_t)(i - 2) * ldu + na * 256); }
;                                        else { ra[i] = (u32x4){0u, 0u, 0u, 0u}; rb[i] = (u32x4){0u, 0u, 0u, 0u}; } }
; #pragma unroll
;         for (int i = 0; i < 8; ++i) {
;             float va[8], vb[8];
; #pragma unroll
;             for (int e = 0; e < 8; ++e) { va[e] = ba[e]; vb[e] = bb[e]; }
; #pragma unroll
;             for (int k = 0; k < 3; ++k) { float xa[8], xb[8]; unpack8(ra[i + k], xa); unpack8(rb[i + k], xb);
; #pragma unroll
;                 for (int e = 0; e < 8; ++e) { va[e] += wa[k][e] * xa[e]; vb[e] += wb[k][e] * xb[e]; } }
;             u32x4 o; { f32x2 gg;
;                 gg = gelu_pk((f32x2){va[0], va[1]}); o.x = cvt_pk_bf16(gg.x * vb[0], gg.y * vb[1]); gg = gelu_pk((f32x2){va[2], va[3]}); o.y = cvt_pk_bf16(gg.x * vb[2], gg.y * vb[3]);
;                 gg = gelu_pk((f32x2){va[4], va[5]}); o.z = cvt_pk_bf16(gg.x * vb[4], gg.y * vb[5]); gg = gelu_pk((f32x2){va[6], va[7]}); o.w = cvt_pk_bf16(gg.x * vb[6], gg.y * vb[7]); }
;             *(u32x4*)(ACT + (size_t)(row0 + i) * FF + j) = o;
.LBB0_33:
	s_or_b64 exec, exec, s[12:13]
	global_load_dwordx4 v[138:141], v[66:67], off
	global_load_dwordx4 v[134:137], v[66:67], off offset:2560
	s_movk_i32 s2, 0x1000
	v_add_co_u32_e32 v68, vcc, s2, v66
	s_movk_i32 s2, 0x3000
	s_nop 0
	v_addc_co_u32_e32 v69, vcc, 0, v67, vcc
	v_add_co_u32_e32 v70, vcc, s3, v66
	s_mov_b32 s16, 0x8000
	s_nop 0
	v_addc_co_u32_e32 v71, vcc, 0, v67, vcc
	v_add_co_u32_e32 v72, vcc, s2, v66
	s_movk_i32 s2, 0x4000
	s_nop 0
	v_addc_co_u32_e32 v73, vcc, 0, v67, vcc
	v_add_co_u32_e32 v74, vcc, s2, v66
	s_movk_i32 s2, 0x6000
	s_nop 0
	v_addc_co_u32_e32 v75, vcc, 0, v67, vcc
	v_add_co_u32_e32 v76, vcc, s19, v66
	s_waitcnt vmcnt(0)
	v_lshlrev_b32_e32 v148, 16, v123
	v_addc_co_u32_e32 v77, vcc, 0, v67, vcc
	v_add_co_u32_e32 v78, vcc, s2, v66
	s_movk_i32 s2, 0x7000
	s_nop 0
	v_addc_co_u32_e32 v79, vcc, 0, v67, vcc
	v_add_co_u32_e32 v80, vcc, s2, v66
	s_mov_b32 s2, 0x9000
	s_nop 0
	v_addc_co_u32_e32 v81, vcc, 0, v67, vcc
	v_add_co_u32_e32 v146, vcc, s16, v66
	v_and_b32_e32 v149, 0xffff0000, v123
	s_nop 0
	v_addc_co_u32_e32 v147, vcc, 0, v67, vcc
	v_add_co_u32_e32 v66, vcc, s2, v66
	v_lshlrev_b32_e32 v150, 16, v117
	s_nop 0
	v_addc_co_u32_e32 v67, vcc, 0, v67, vcc
	v_and_b32_e32 v151, 0xffff0000, v117
	v_lshlrev_b32_e32 v160, 16, v122
	v_and_b32_e32 v161, 0xffff0000, v122
	v_lshlrev_b32_e32 v156, 16, v116
	v_and_b32_e32 v157, 0xffff0000, v116
	global_load_dwordx4 v[122:125], v[68:69], off offset:1024
	global_load_dwordx4 v[116:119], v[68:69], off offset:3584
	global_load_dwordx4 v[110:113], v[70:71], off offset:2048
	global_load_dwordx4 v[106:109], v[72:73], off offset:512
	global_load_dwordx4 v[102:105], v[72:73], off offset:3072
	global_load_dwordx4 v[98:101], v[74:75], off offset:1536
	global_load_dwordx4 v[94:97], v[76:77], off
	global_load_dwordx4 v[90:93], v[76:77], off offset:2560
	global_load_dwordx4 v[86:89], v[78:79], off offset:1024
	global_load_dwordx4 v[82:85], v[78:79], off offset:3584
	s_nop 0
	global_load_dwordx4 v[78:81], v[80:81], off offset:2048
	s_nop 0
	global_load_dwordx4 v[74:77], v[146:147], off offset:512
	s_nop 0
	global_load_dwordx4 v[66:69], v[66:67], off offset:1536
	s_nop 0
	global_load_dwordx4 v[70:73], v[146:147], off offset:3072
	s_waitcnt vmcnt(16)
	v_lshlrev_b32_e32 v154, 16, v129
	v_and_b32_e32 v155, 0xffff0000, v129
	v_lshlrev_b32_e32 v152, 16, v133
	v_and_b32_e32 v153, 0xffff0000, v133
	v_lshlrev_b32_e32 v162, 16, v128
	v_and_b32_e32 v163, 0xffff0000, v128
	v_lshlrev_b32_e32 v158, 16, v132
	v_and_b32_e32 v159, 0xffff0000, v132
	v_pk_fma_f32 v[132:133], v[32:33], v[154:155], v[64:65]
	v_pk_fma_f32 v[128:129], v[28:29], v[148:149], v[60:61]
	v_pk_fma_f32 v[146:147], v[26:27], v[160:161], v[58:59]
	v_pk_fma_f32 v[160:161], v[30:31], v[162:163], v[62:63]
	v_pk_fma_f32 v[132:133], v[48:49], v[152:153], v[132:133]
	v_pk_fma_f32 v[160:161], v[46:47], v[158:159], v[160:161]
	v_pk_fma_f32 v[128:129], v[36:37], v[150:151], v[128:129]
	v_pk_fma_f32 v[162:163], v[34:35], v[156:157], v[146:147]
	v_lshlrev_b32_e32 v178, 16, v114
	v_and_b32_e32 v179, 0xffff0000, v114
	v_lshlrev_b32_e32 v180, 16, v130
	v_and_b32_e32 v181, 0xffff0000, v130
	s_mov_b32 s2, 0xbf3a00e3
	v_lshl_add_u64 v[144:145], v[0:1], 1, s[42:43]
	v_or_b32_e32 v0, 1, v164
	v_add_u32_e32 v143, s33, v143
	v_add_u32_e32 v142, s15, v142
	v_subrev_u32_e32 v188, 0x40000, v143
	v_mov_b32_e32 v190, s33
	v_mov_b32_e32 v191, 0x7ffffff0
	v_cmp_ne_u32_e32 vcc, 0x20000, v190
	v_lshrrev_b32_e32 v189, 9, v188
	v_lshlrev_b32_e32 v189, 8, v189
	v_cndmask_b32_e32 v188, v188, v191, vcc
	v_sub_u32_e32 v189, v188, v189
	v_and_b32_e32 v190, 0x100, v188
	v_add_u32_e32 v189, 0x40000, v189
	v_cmp_eq_u32_e32 vcc, 0, v190
	s_nop 1
	v_cndmask_b32_e32 v189, v191, v189, vcc
	v_cmp_gt_u32_e32 vcc, 0x20000, v188
	s_nop 1
	v_cndmask_b32_e32 v143, v143, v189, vcc
	v_lshlrev_b32_e32 v142, 3, v143
	s_waitcnt vmcnt(15)
	v_lshlrev_b32_e32 v146, 16, v141
	s_waitcnt vmcnt(14)
	v_lshlrev_b32_e32 v148, 16, v137
	v_and_b32_e32 v149, 0xffff0000, v137
	v_pk_fma_f32 v[154:155], v[56:57], v[148:149], v[132:133]
	v_lshlrev_b32_e32 v132, 16, v136
	v_and_b32_e32 v133, 0xffff0000, v136
	v_lshlrev_b32_e32 v136, 16, v121
	v_and_b32_e32 v137, 0xffff0000, v121
	v_pk_fma_f32 v[172:173], v[54:55], v[132:133], v[160:161]
	v_pk_fma_f32 v[136:137], v[4:5], v[136:137], v[40:41]
	v_lshlrev_b32_e32 v160, 16, v115
	v_and_b32_e32 v161, 0xffff0000, v115
	v_pk_fma_f32 v[166:167], v[12:13], v[160:161], v[136:137]
	v_lshlrev_b32_e32 v136, 16, v139
	v_and_b32_e32 v137, 0xffff0000, v139
	v_and_b32_e32 v147, 0xffff0000, v141
	v_pk_fma_f32 v[176:177], v[20:21], v[136:137], v[166:167]
	v_lshlrev_b32_e32 v166, 16, v120
	v_and_b32_e32 v167, 0xffff0000, v120
	v_lshlrev_b32_e32 v120, 16, v126
	v_and_b32_e32 v121, 0xffff0000, v126
	v_pk_fma_f32 v[170:171], v[52:53], v[146:147], v[128:129]
	v_lshlrev_b32_e32 v128, 16, v140
	v_and_b32_e32 v129, 0xffff0000, v140
	v_lshlrev_b32_e32 v140, 16, v127
	v_and_b32_e32 v141, 0xffff0000, v127
	v_pk_fma_f32 v[126:127], v[2:3], v[166:167], v[38:39]
	v_pk_fma_f32 v[120:121], v[6:7], v[120:121], v[42:43]
	v_pk_fma_f32 v[168:169], v[50:51], v[128:129], v[162:163]
	v_lshlrev_b32_e32 v162, 16, v131
	v_and_b32_e32 v163, 0xffff0000, v131
	v_pk_fma_f32 v[114:115], v[10:11], v[178:179], v[126:127]
	v_pk_fma_f32 v[130:131], v[22:23], v[180:181], v[120:121]
	v_lshlrev_b32_e32 v120, 16, v138
	v_and_b32_e32 v121, 0xffff0000, v138
	v_pk_fma_f32 v[138:139], v[18:19], v[120:121], v[114:115]
	v_and_b32_e32 v183, 0x7fffffff, v177
	v_and_b32_e32 v115, 0x7fffffff, v139
	v_and_b32_e32 v114, 0x7fffffff, v138
	v_pk_fma_f32 v[114:115], v[114:115], s[14:15], 1.0 op_sel_hi:[1,0,0]
; __device__ __forceinline__ unsigned cvt_pk_bf16(float lo, float hi) { f32x2 v = {lo, hi}; bf16x2_t b = __builtin_convertvector(v, bf16x2_t); return __builtin_bit_cast(unsigned, b); }
; __device__ __forceinline__ void unpack8(const u32x4& r, float (&v)[8]) { v[0] = bf_lo(r.x); v[1] = bf_hi(r.x); v[2] = bf_lo(r.y); v[3] = bf_hi(r.y); v[4] = bf_lo(r.z); v[5] = bf_hi(r.z); v[6] = bf_lo(r.w); v[7] = bf_hi(r.w); }
; __device__ __forceinline__ f32x2 gelu_pk(f32x2 v) {
;     const f32x2 av = __builtin_elementwise_abs(v), d = av * 0.2316418882f + 1.0f;
;     f32x2 t; t.x = __builtin_amdgcn_rcpf(d.x); t.y = __builtin_amdgcn_rcpf(d.y);
;     f32x2 q = t * 0.5307027145f + (-0.7265760135f); q = q * t + 0.7107068705f; q = q * t + (-0.142248368f); q = q * t + 0.127414796f; q = q * t;
;     const f32x2 s = (v * v) * (-0.72134752044f);
;     f32x2 e; e.x = __builtin_amdgcn_exp2f(s.x); e.y = __builtin_amdgcn_exp2f(s.y);
;     const f32x2 m = v * (q * e), r = v - m;
;     f32x2 o; o.x = v.x < 0.f ? m.x : r.x; o.y = v.y < 0.f ? m.y : r.y; return o;
; }
; __device__ __forceinline__ void conv_phase(KP kp, int l, int a0t, int na) {
;     ...
;             for (int k = 0; k < 3; ++k) { float xa[8], xb[8]; unpack8(ra[i + k], xa); unpack8(rb[i + k], xb);
; #pragma unroll
;                 for (int e = 0; e < 8; ++e) { va[e] += wa[k][e] * xa[e]; vb[e] += wb[k][e] * xb[e]; } }
;             u32x4 o; { f32x2 gg;
;                 gg = gelu_pk((f32x2){va[0], va[1]}); o.x = cvt_pk_bf16(gg.x * vb[0], gg.y * vb[1]); gg = gelu_pk((f32x2){va[2], va[3]}); o.y = cvt_pk_bf16(gg.x * vb[2], gg.y * vb[3]);
;                 gg = gelu_pk((f32x2){va[4], va[5]}); o.z = cvt_pk_bf16(gg.x * vb[4], gg.y * vb[5]); gg = gelu_pk((f32x2){va[6], va[7]}); o.w = cvt_pk_bf16(gg.x * vb[6], gg.y * vb[7]); }
;             *(u32x4*)(ACT + (size_t)(row0 + i) * FF + j) = o;
	v_and_b32_e32 v182, 0x7fffffff, v176
	v_rcp_f32_e32 v166, v114
	v_rcp_f32_e32 v167, v115
	v_pk_fma_f32 v[140:141], v[8:9], v[140:141], v[44:45]
	v_mov_b64_e32 v[114:115], s[2:3]
	v_pk_fma_f32 v[182:183], v[182:183], s[14:15], 1.0 op_sel_hi:[1,0,0]
	v_pk_fma_f32 v[174:175], v[24:25], v[162:163], v[140:141]
	v_lshlrev_b32_e32 v140, 16, v135
	v_and_b32_e32 v141, 0xffff0000, v135
	v_lshlrev_b32_e32 v126, 16, v134
	v_and_b32_e32 v127, 0xffff0000, v134
	v_pk_fma_f32 v[134:135], v[166:167], s[38:39], v[114:115] op_sel_hi:[1,0,0]
	v_rcp_f32_e32 v182, v182
	v_rcp_f32_e32 v183, v183
	v_pk_fma_f32 v[134:135], v[166:167], v[134:135], s[10:11] op_sel_hi:[1,1,0]
	v_and_b32_e32 v185, 0x7fffffff, v169
	v_pk_fma_f32 v[134:135], v[166:167], v[134:135], s[56:57] op_sel_hi:[1,1,0]
	v_and_b32_e32 v184, 0x7fffffff, v168
	v_pk_fma_f32 v[134:135], v[166:167], v[134:135], s[64:65] op_sel_hi:[1,1,0]
	v_pk_fma_f32 v[184:185], v[184:185], s[14:15], 1.0 op_sel_hi:[1,0,0]
	v_pk_mul_f32 v[134:135], v[166:167], v[134:135]
	v_pk_fma_f32 v[166:167], v[182:183], s[38:39], v[114:115] op_sel_hi:[1,0,0]
	v_rcp_f32_e32 v184, v184
	v_rcp_f32_e32 v185, v185
	v_pk_mul_f32 v[186:187], v[138:139], v[138:139]
	v_pk_fma_f32 v[166:167], v[182:183], v[166:167], s[10:11] op_sel_hi:[1,1,0]
	v_pk_mul_f32 v[186:187], v[186:187], s[18:19] op_sel_hi:[1,0]
	v_pk_fma_f32 v[166:167], v[182:183], v[166:167], s[56:57] op_sel_hi:[1,1,0]
	v_exp_f32_e32 v186, v186
	v_exp_f32_e32 v187, v187
	v_pk_fma_f32 v[166:167], v[182:183], v[166:167], s[64:65] op_sel_hi:[1,1,0]
	v_cmp_gt_f32_e32 vcc, 0, v139
	v_pk_mul_f32 v[182:183], v[182:183], v[166:167]
	v_pk_fma_f32 v[166:167], v[184:185], s[38:39], v[114:115] op_sel_hi:[1,0,0]
	v_pk_mul_f32 v[134:135], v[186:187], v[134:135]
	v_pk_fma_f32 v[166:167], v[184:185], v[166:167], s[10:11] op_sel_hi:[1,1,0]
	v_pk_mul_f32 v[186:187], v[176:177], v[176:177]
	v_pk_fma_f32 v[166:167], v[184:185], v[166:167], s[56:57] op_sel_hi:[1,1,0]
	v_pk_mul_f32 v[186:187], v[186:187], s[18:19] op_sel_hi:[1,0]
	v_pk_fma_f32 v[166:167], v[184:185], v[166:167], s[64:65] op_sel_hi:[1,1,0]
	v_exp_f32_e32 v186, v186
	v_pk_mul_f32 v[184:185], v[184:185], v[166:167]
	v_pk_mul_f32 v[166:167], v[138:139], v[134:135]
	v_pk_fma_f32 v[134:135], v[138:139], v[134:135], v[138:139] neg_lo:[1,0,0] neg_hi:[1,0,0]
	v_exp_f32_e32 v187, v187
	v_cndmask_b32_e32 v135, v135, v167, vcc
	v_cmp_gt_f32_e32 vcc, 0, v138
	v_pk_fma_f32 v[130:131], v[14:15], v[126:127], v[130:131]
	v_pk_mul_f32 v[138:139], v[168:169], v[168:169]
	v_cndmask_b32_e32 v134, v134, v166, vcc
	v_pk_mul_f32 v[130:131], v[130:131], v[134:135]
	v_pk_mul_f32 v[138:139], v[138:139], s[18:19] op_sel_hi:[1,0]
	v_cvt_pk_bf16_f32 v166, v130, v131
	v_pk_mul_f32 v[130:131], v[186:187], v[182:183]
	v_cmp_gt_f32_e32 vcc, 0, v177
	v_pk_mul_f32 v[134:135], v[176:177], v[130:131]
	v_pk_fma_f32 v[130:131], v[176:177], v[130:131], v[176:177] neg_lo:[1,0,0] neg_hi:[1,0,0]
	v_exp_f32_e32 v138, v138
	v_exp_f32_e32 v139, v139
	v_cndmask_b32_e32 v131, v131, v135, vcc
	v_cmp_gt_f32_e32 vcc, 0, v176
	v_pk_fma_f32 v[174:175], v[16:17], v[140:141], v[174:175]
	s_movk_i32 s2, 0x1600
	v_cndmask_b32_e32 v130, v130, v134, vcc
	v_pk_mul_f32 v[130:131], v[174:175], v[130:131]
	v_cmp_gt_f32_e32 vcc, 0, v169
	v_cvt_pk_bf16_f32 v167, v130, v131
	v_pk_mul_f32 v[130:131], v[138:139], v[184:185]
	v_and_b32_e32 v139, 0x7fffffff, v171
	v_and_b32_e32 v138, 0x7fffffff, v170
	v_pk_fma_f32 v[138:139], v[138:139], s[14:15], 1.0 op_sel_hi:[1,0,0]
	v_pk_mul_f32 v[134:135], v[168:169], v[130:131]
	v_pk_fma_f32 v[130:131], v[168:169], v[130:131], v[168:169] neg_lo:[1,0,0] neg_hi:[1,0,0]
	v_rcp_f32_e32 v138, v138
	v_rcp_f32_e32 v139, v139
	v_cndmask_b32_e32 v131, v131, v135, vcc
	v_cmp_gt_f32_e32 vcc, 0, v168
	s_nop 1
	v_cndmask_b32_e32 v130, v130, v134, vcc
	v_pk_mul_f32 v[130:131], v[172:173], v[130:131]
	v_pk_mul_f32 v[134:135], v[170:171], v[170:171]
	v_cvt_pk_bf16_f32 v168, v130, v131
	v_pk_fma_f32 v[130:131], v[138:139], s[38:39], v[114:115] op_sel_hi:[1,0,0]
	v_pk_mul_f32 v[134:135], v[134:135], s[18:19] op_sel_hi:[1,0]
	v_pk_fma_f32 v[130:131], v[138:139], v[130:131], s[10:11] op_sel_hi:[1,1,0]
	v_exp_f32_e32 v134, v134
	v_exp_f32_e32 v135, v135
	v_pk_fma_f32 v[130:131], v[138:139], v[130:131], s[56:57] op_sel_hi:[1,1,0]
	v_cmp_gt_f32_e32 vcc, 0, v171
	v_pk_fma_f32 v[130:131], v[138:139], v[130:131], s[64:65] op_sel_hi:[1,1,0]
	s_nop 0
	v_pk_mul_f32 v[130:131], v[138:139], v[130:131]
	s_waitcnt vmcnt(13)
	v_lshlrev_b32_e32 v138, 16, v125
	v_pk_mul_f32 v[130:131], v[134:135], v[130:131]
	v_and_b32_e32 v139, 0xffff0000, v125
	v_pk_mul_f32 v[134:135], v[170:171], v[130:131]
	v_pk_fma_f32 v[130:131], v[170:171], v[130:131], v[170:171] neg_lo:[1,0,0] neg_hi:[1,0,0]
	s_nop 0
	v_cndmask_b32_e32 v131, v131, v135, vcc
	v_cmp_gt_f32_e32 vcc, 0, v170
	s_nop 1
	v_cndmask_b32_e32 v130, v130, v134, vcc
	v_pk_mul_f32 v[130:131], v[154:155], v[130:131]
	v_pk_fma_f32 v[134:135], v[32:33], v[152:153], v[64:65]
	v_cvt_pk_bf16_f32 v169, v130, v131
	v_mad_i64_i32 v[130:131], s[12:13], v164, s2, v[144:145]
	global_store_dwordx4 v[130:131], v[166:169], off
	v_pk_fma_f32 v[130:131], v[28:29], v[150:151], v[60:61]
	v_pk_fma_f32 v[134:135], v[48:49], v[148:149], v[134:135]
	v_pk_fma_f32 v[130:131], v[36:37], v[146:147], v[130:131]
	s_waitcnt vmcnt(13)
; __device__ __forceinline__ unsigned cvt_pk_bf16(float lo, float hi) { f32x2 v = {lo, hi}; bf16x2_t b = __builtin_convertvector(v, bf16x2_t); return __builtin_bit_cast(unsigned, b); }
; __device__ __forceinline__ void unpack8(const u32x4& r, float (&v)[8]) { v[0] = bf_lo(r.x); v[1] = bf_hi(r.x); v[2] = bf_lo(r.y); v[3] = bf_hi(r.y); v[4] = bf_lo(r.z); v[5] = bf_hi(r.z); v[6] = bf_lo(r.w); v[7] = bf_hi(r.w); }
; __device__ __forceinline__ f32x2 gelu_pk(f32x2 v) {
;     const f32x2 av = __builtin_elementwise_abs(v), d = av * 0.2316418882f + 1.0f;
;     f32x2 t; t.x = __builtin_amdgcn_rcpf(d.x); t.y = __builtin_amdgcn_rcpf(d.y);
;     f32x2 q = t * 0.5307027145f + (-0.7265760135f); q = q * t + 0.7107068705f; q = q * t + (-0.142248368f); q = q * t + 0.127414796f; q = q * t;
;     const f32x2 s = (v * v) * (-0.72134752044f);
;     f32x2 e; e.x = __builtin_amdgcn_exp2f(s.x); e.y = __builtin_amdgcn_exp2f(s.y);
;     const f32x2 m = v * (q * e), r = v - m;
;     f32x2 o; o.x = v.x < 0.f ? m.x : r.x; o.y = v.y < 0.f ? m.y : r.y; return o;
; }
; __device__ __forceinline__ void conv_phase(KP kp, int l, int a0t, int na) {
;     ...
;             for (int k = 0; k < 3; ++k) { float xa[8], xb[8]; unpack8(ra[i + k], xa); unpack8(rb[i + k], xb);
; #pragma unroll
;                 for (int e = 0; e < 8; ++e) { va[e] += wa[k][e] * xa[e]; vb[e] += wb[k][e] * xb[e]; } }
;             u32x4 o; { f32x2 gg;
;                 gg = gelu_pk((f32x2){va[0], va[1]}); o.x = cvt_pk_bf16(gg.x * vb[0], gg.y * vb[1]); gg = gelu_pk((f32x2){va[2], va[3]}); o.y = cvt_pk_bf16(gg.x * vb[2], gg.y * vb[3]);
;                 gg = gelu_pk((f32x2){va[4], va[5]}); o.z = cvt_pk_bf16(gg.x * vb[4], gg.y * vb[5]); gg = gelu_pk((f32x2){va[6], va[7]}); o.w = cvt_pk_bf16(gg.x * vb[6], gg.y * vb[7]); }
;             *(u32x4*)(ACT + (size_t)(row0 + i) * FF + j) = o;
	v_lshlrev_b32_e32 v154, 16, v119
	v_and_b32_e32 v155, 0xffff0000, v119
	v_pk_fma_f32 v[166:167], v[52:53], v[138:139], v[130:131]
	v_pk_fma_f32 v[168:169], v[56:57], v[154:155], v[134:135]
	v_pk_fma_f32 v[130:131], v[26:27], v[156:157], v[58:59]
	v_pk_fma_f32 v[134:135], v[30:31], v[158:159], v[62:63]
	v_pk_fma_f32 v[130:131], v[34:35], v[128:129], v[130:131]
	v_pk_fma_f32 v[150:151], v[46:47], v[132:133], v[134:135]
	v_lshlrev_b32_e32 v134, 16, v124
	v_and_b32_e32 v135, 0xffff0000, v124
	v_lshlrev_b32_e32 v152, 16, v118
	v_and_b32_e32 v153, 0xffff0000, v118
	v_pk_fma_f32 v[118:119], v[50:51], v[134:135], v[130:131]
	v_pk_fma_f32 v[124:125], v[4:5], v[160:161], v[40:41]
	v_pk_fma_f32 v[130:131], v[8:9], v[162:163], v[44:45]
	v_pk_fma_f32 v[124:125], v[12:13], v[136:137], v[124:125]
	v_pk_fma_f32 v[156:157], v[24:25], v[140:141], v[130:131]
	v_lshlrev_b32_e32 v130, 16, v123
	v_and_b32_e32 v131, 0xffff0000, v123
	v_pk_fma_f32 v[160:161], v[20:21], v[130:131], v[124:125]
	v_pk_fma_f32 v[124:125], v[2:3], v[178:179], v[38:39]
	v_pk_fma_f32 v[158:159], v[54:55], v[152:153], v[150:151]
	v_lshlrev_b32_e32 v150, 16, v117
	v_and_b32_e32 v151, 0xffff0000, v117
	v_pk_fma_f32 v[170:171], v[10:11], v[120:121], v[124:125]
	v_lshlrev_b32_e32 v124, 16, v122
	v_and_b32_e32 v125, 0xffff0000, v122
	v_pk_fma_f32 v[162:163], v[16:17], v[150:151], v[156:157]
	v_pk_fma_f32 v[156:157], v[6:7], v[180:181], v[42:43]
	v_pk_fma_f32 v[122:123], v[18:19], v[124:125], v[170:171]
	v_pk_fma_f32 v[172:173], v[22:23], v[126:127], v[156:157]
	v_and_b32_e32 v157, 0x7fffffff, v123
	v_and_b32_e32 v156, 0x7fffffff, v122
	v_pk_fma_f32 v[156:157], v[156:157], s[14:15], 1.0 op_sel_hi:[1,0,0]
	v_and_b32_e32 v175, 0x7fffffff, v161
	v_rcp_f32_e32 v170, v156
	v_rcp_f32_e32 v171, v157
	v_and_b32_e32 v174, 0x7fffffff, v160
	v_lshlrev_b32_e32 v156, 16, v116
	v_and_b32_e32 v157, 0xffff0000, v116
	v_pk_fma_f32 v[174:175], v[174:175], s[14:15], 1.0 op_sel_hi:[1,0,0]
	v_pk_fma_f32 v[116:117], v[14:15], v[156:157], v[172:173]
	v_pk_fma_f32 v[172:173], v[170:171], s[38:39], v[114:115] op_sel_hi:[1,0,0]
	v_rcp_f32_e32 v174, v174
	v_rcp_f32_e32 v175, v175
	v_pk_fma_f32 v[172:173], v[170:171], v[172:173], s[10:11] op_sel_hi:[1,1,0]
	v_and_b32_e32 v177, 0x7fffffff, v119
	v_pk_fma_f32 v[172:173], v[170:171], v[172:173], s[56:57] op_sel_hi:[1,1,0]
	v_and_b32_e32 v176, 0x7fffffff, v118
	v_pk_fma_f32 v[172:173], v[170:171], v[172:173], s[64:65] op_sel_hi:[1,1,0]
	v_pk_fma_f32 v[176:177], v[176:177], s[14:15], 1.0 op_sel_hi:[1,0,0]
	v_pk_mul_f32 v[178:179], v[122:123], v[122:123]
	v_pk_mul_f32 v[170:171], v[170:171], v[172:173]
	v_pk_fma_f32 v[172:173], v[174:175], s[38:39], v[114:115] op_sel_hi:[1,0,0]
	v_rcp_f32_e32 v176, v176
	v_rcp_f32_e32 v177, v177
	v_pk_mul_f32 v[178:179], v[178:179], s[18:19] op_sel_hi:[1,0]
	v_pk_fma_f32 v[172:173], v[174:175], v[172:173], s[10:11] op_sel_hi:[1,1,0]
	v_exp_f32_e32 v178, v178
	v_exp_f32_e32 v179, v179
	v_pk_fma_f32 v[172:173], v[174:175], v[172:173], s[56:57] op_sel_hi:[1,1,0]
	v_cmp_gt_f32_e32 vcc, 0, v123
	v_pk_fma_f32 v[172:173], v[174:175], v[172:173], s[64:65] op_sel_hi:[1,1,0]
	v_pk_mul_f32 v[170:171], v[178:179], v[170:171]
	v_pk_mul_f32 v[172:173], v[174:175], v[172:173]
	v_pk_fma_f32 v[174:175], v[176:177], s[38:39], v[114:115] op_sel_hi:[1,0,0]
	v_pk_mul_f32 v[178:179], v[160:161], v[160:161]
	v_pk_fma_f32 v[174:175], v[176:177], v[174:175], s[10:11] op_sel_hi:[1,1,0]
	v_pk_mul_f32 v[178:179], v[178:179], s[18:19] op_sel_hi:[1,0]
	v_pk_fma_f32 v[174:175], v[176:177], v[174:175], s[56:57] op_sel_hi:[1,1,0]
	v_exp_f32_e32 v178, v178
	v_pk_fma_f32 v[174:175], v[176:177], v[174:175], s[64:65] op_sel_hi:[1,1,0]
	v_exp_f32_e32 v179, v179
	v_pk_mul_f32 v[174:175], v[176:177], v[174:175]
	v_pk_mul_f32 v[176:177], v[122:123], v[170:171]
	v_pk_fma_f32 v[170:171], v[122:123], v[170:171], v[122:123] neg_lo:[1,0,0] neg_hi:[1,0,0]
	s_nop 0
	v_cndmask_b32_e32 v123, v171, v177, vcc
	v_cmp_gt_f32_e32 vcc, 0, v122
	s_nop 1
	v_cndmask_b32_e32 v122, v170, v176, vcc
	v_pk_mul_f32 v[116:117], v[116:117], v[122:123]
	v_pk_mul_f32 v[122:123], v[178:179], v[172:173]
	v_pk_mul_f32 v[172:173], v[118:119], v[118:119]
	v_pk_mul_f32 v[170:171], v[160:161], v[122:123]
	v_pk_mul_f32 v[172:173], v[172:173], s[18:19] op_sel_hi:[1,0]
	v_pk_fma_f32 v[122:123], v[160:161], v[122:123], v[160:161] neg_lo:[1,0,0] neg_hi:[1,0,0]
	v_cmp_gt_f32_e32 vcc, 0, v161
	v_exp_f32_e32 v172, v172
	v_exp_f32_e32 v173, v173
	v_cndmask_b32_e32 v123, v123, v171, vcc
	v_cmp_gt_f32_e32 vcc, 0, v160
	v_cvt_pk_bf16_f32 v116, v116, v117
	s_nop 0
	v_cndmask_b32_e32 v122, v122, v170, vcc
	v_pk_mul_f32 v[122:123], v[162:163], v[122:123]
	v_and_b32_e32 v163, 0x7fffffff, v167
	v_and_b32_e32 v162, 0x7fffffff, v166
	v_cvt_pk_bf16_f32 v117, v122, v123
	v_pk_mul_f32 v[122:123], v[172:173], v[174:175]
	v_pk_fma_f32 v[162:163], v[162:163], s[14:15], 1.0 op_sel_hi:[1,0,0]
	v_pk_mul_f32 v[160:161], v[118:119], v[122:123]
	v_pk_fma_f32 v[122:123], v[118:119], v[122:123], v[118:119] neg_lo:[1,0,0] neg_hi:[1,0,0]
	v_cmp_gt_f32_e32 vcc, 0, v119
	v_rcp_f32_e32 v162, v162
	v_rcp_f32_e32 v163, v163
	v_cndmask_b32_e32 v119, v123, v161, vcc
	v_cmp_gt_f32_e32 vcc, 0, v118
	s_nop 1
	v_cndmask_b32_e32 v118, v122, v160, vcc
	v_pk_mul_f32 v[118:119], v[158:159], v[118:119]
	v_pk_mul_f32 v[158:159], v[166:167], v[166:167]
	v_pk_fma_f32 v[122:123], v[162:163], s[38:39], v[114:115] op_sel_hi:[1,0,0]
	v_pk_mul_f32 v[158:159], v[158:159], s[18:19] op_sel_hi:[1,0]
	v_pk_fma_f32 v[122:123], v[162:163], v[122:123], s[10:11] op_sel_hi:[1,1,0]
	v_exp_f32_e32 v158, v158
	v_exp_f32_e32 v159, v159
	v_pk_fma_f32 v[122:123], v[162:163], v[122:123], s[56:57] op_sel_hi:[1,1,0]
	v_cmp_gt_f32_e32 vcc, 0, v167
	v_pk_fma_f32 v[122:123], v[162:163], v[122:123], s[64:65] op_sel_hi:[1,1,0]
	v_cvt_pk_bf16_f32 v118, v118, v119
	v_pk_mul_f32 v[122:123], v[162:163], v[122:123]
	s_nop 0
	v_pk_mul_f32 v[122:123], v[158:159], v[122:123]
	s_nop 0
	v_pk_mul_f32 v[158:159], v[166:167], v[122:123]
	v_pk_fma_f32 v[122:123], v[166:167], v[122:123], v[166:167] neg_lo:[1,0,0] neg_hi:[1,0,0]
	s_nop 0
	v_cndmask_b32_e32 v123, v123, v159, vcc
	v_cmp_gt_f32_e32 vcc, 0, v166
	s_nop 1
	v_cndmask_b32_e32 v122, v122, v158, vcc
	v_pk_mul_f32 v[122:123], v[168:169], v[122:123]
	s_nop 0
	v_cvt_pk_bf16_f32 v119, v122, v123
	v_mad_i64_i32 v[122:123], s[12:13], v0, s2, v[144:145]
	global_store_dwordx4 v[122:123], v[116:119], off
	s_waitcnt vmcnt(13)
; __device__ __forceinline__ unsigned cvt_pk_bf16(float lo, float hi) { f32x2 v = {lo, hi}; bf16x2_t b = __builtin_convertvector(v, bf16x2_t); return __builtin_bit_cast(unsigned, b); }
; __device__ __forceinline__ void unpack8(const u32x4& r, float (&v)[8]) { v[0] = bf_lo(r.x); v[1] = bf_hi(r.x); v[2] = bf_lo(r.y); v[3] = bf_hi(r.y); v[4] = bf_lo(r.z); v[5] = bf_hi(r.z); v[6] = bf_lo(r.w); v[7] = bf_hi(r.w); }
; __device__ __forceinline__ f32x2 gelu_pk(f32x2 v) {
;     const f32x2 av = __builtin_elementwise_abs(v), d = av * 0.2316418882f + 1.0f;
;     f32x2 t; t.x = __builtin_amdgcn_rcpf(d.x); t.y = __builtin_amdgcn_rcpf(d.y);
;     f32x2 q = t * 0.5307027145f + (-0.7265760135f); q = q * t + 0.7107068705f; q = q * t + (-0.142248368f); q = q * t + 0.127414796f; q = q * t;
;     const f32x2 s = (v * v) * (-0.72134752044f);
;     f32x2 e; e.x = __builtin_amdgcn_exp2f(s.x); e.y = __builtin_amdgcn_exp2f(s.y);
;     const f32x2 m = v * (q * e), r = v - m;
;     f32x2 o; o.x = v.x < 0.f ? m.x : r.x; o.y = v.y < 0.f ? m.y : r.y; return o;
; }
; __device__ __forceinline__ void conv_phase(KP kp, int l, int a0t, int na) {
;     ...
;             for (int k = 0; k < 3; ++k) { float xa[8], xb[8]; unpack8(ra[i + k], xa); unpack8(rb[i + k], xb);
; #pragma unroll
;                 for (int e = 0; e < 8; ++e) { va[e] += wa[k][e] * xa[e]; vb[e] += wb[k][e] * xb[e]; } }
;             u32x4 o; { f32x2 gg;
;                 gg = gelu_pk((f32x2){va[0], va[1]}); o.x = cvt_pk_bf16(gg.x * vb[0], gg.y * vb[1]); gg = gelu_pk((f32x2){va[2], va[3]}); o.y = cvt_pk_bf16(gg.x * vb[2], gg.y * vb[3]);
;                 gg = gelu_pk((f32x2){va[4], va[5]}); o.z = cvt_pk_bf16(gg.x * vb[4], gg.y * vb[5]); gg = gelu_pk((f32x2){va[6], va[7]}); o.w = cvt_pk_bf16(gg.x * vb[6], gg.y * vb[7]); }
;             *(u32x4*)(ACT + (size_t)(row0 + i) * FF + j) = o;
	v_lshlrev_b32_e32 v122, 16, v113
	v_and_b32_e32 v123, 0xffff0000, v113
	v_pk_fma_f32 v[116:117], v[28:29], v[146:147], v[60:61]
	v_pk_fma_f32 v[118:119], v[32:33], v[148:149], v[64:65]
	v_pk_fma_f32 v[116:117], v[36:37], v[138:139], v[116:117]
	v_pk_fma_f32 v[118:119], v[48:49], v[154:155], v[118:119]
	s_waitcnt vmcnt(12)
	v_lshlrev_b32_e32 v148, 16, v109
	v_and_b32_e32 v149, 0xffff0000, v109
	v_pk_fma_f32 v[158:159], v[52:53], v[122:123], v[116:117]
	v_pk_fma_f32 v[160:161], v[56:57], v[148:149], v[118:119]
	v_pk_fma_f32 v[116:117], v[26:27], v[128:129], v[58:59]
	v_pk_fma_f32 v[118:119], v[30:31], v[132:133], v[62:63]
	v_pk_fma_f32 v[116:117], v[34:35], v[134:135], v[116:117]
	v_pk_fma_f32 v[128:129], v[46:47], v[152:153], v[118:119]
	v_lshlrev_b32_e32 v118, 16, v112
	v_and_b32_e32 v119, 0xffff0000, v112
	v_lshlrev_b32_e32 v146, 16, v108
	v_and_b32_e32 v147, 0xffff0000, v108
	v_pk_fma_f32 v[108:109], v[50:51], v[118:119], v[116:117]
	v_pk_fma_f32 v[112:113], v[4:5], v[136:137], v[40:41]
	v_pk_fma_f32 v[116:117], v[8:9], v[140:141], v[44:45]
	v_pk_fma_f32 v[112:113], v[12:13], v[130:131], v[112:113]
	v_pk_fma_f32 v[132:133], v[24:25], v[150:151], v[116:117]
	v_lshlrev_b32_e32 v116, 16, v111
	v_and_b32_e32 v117, 0xffff0000, v111
	v_pk_fma_f32 v[162:163], v[20:21], v[116:117], v[112:113]
	v_pk_fma_f32 v[112:113], v[2:3], v[120:121], v[38:39]
	v_pk_fma_f32 v[120:121], v[6:7], v[126:127], v[42:43]
	v_pk_fma_f32 v[126:127], v[10:11], v[124:125], v[112:113]
	v_lshlrev_b32_e32 v112, 16, v110
	v_and_b32_e32 v113, 0xffff0000, v110
	v_pk_fma_f32 v[110:111], v[18:19], v[112:113], v[126:127]
	v_and_b32_e32 v167, 0x7fffffff, v163
	v_and_b32_e32 v127, 0x7fffffff, v111
	v_and_b32_e32 v126, 0x7fffffff, v110
	v_pk_fma_f32 v[126:127], v[126:127], s[14:15], 1.0 op_sel_hi:[1,0,0]
	v_and_b32_e32 v166, 0x7fffffff, v162
	v_rcp_f32_e32 v126, v126
	v_rcp_f32_e32 v127, v127
	v_pk_fma_f32 v[120:121], v[22:23], v[156:157], v[120:121]
	v_lshlrev_b32_e32 v140, 16, v106
	v_and_b32_e32 v141, 0xffff0000, v106
	v_pk_fma_f32 v[166:167], v[166:167], s[14:15], 1.0 op_sel_hi:[1,0,0]
	v_lshlrev_b32_e32 v136, 16, v107
	v_and_b32_e32 v137, 0xffff0000, v107
	v_pk_fma_f32 v[106:107], v[14:15], v[140:141], v[120:121]
	v_pk_fma_f32 v[120:121], v[126:127], s[38:39], v[114:115] op_sel_hi:[1,0,0]
	v_rcp_f32_e32 v166, v166
	v_rcp_f32_e32 v167, v167
	v_pk_fma_f32 v[120:121], v[126:127], v[120:121], s[10:11] op_sel_hi:[1,1,0]
	v_and_b32_e32 v169, 0x7fffffff, v109
	v_pk_fma_f32 v[120:121], v[126:127], v[120:121], s[56:57] op_sel_hi:[1,1,0]
	v_and_b32_e32 v168, 0x7fffffff, v108
	v_pk_fma_f32 v[120:121], v[126:127], v[120:121], s[64:65] op_sel_hi:[1,1,0]
	v_pk_fma_f32 v[168:169], v[168:169], s[14:15], 1.0 op_sel_hi:[1,0,0]
	v_pk_mul_f32 v[170:171], v[110:111], v[110:111]
	v_pk_mul_f32 v[120:121], v[126:127], v[120:121]
	v_pk_fma_f32 v[126:127], v[166:167], s[38:39], v[114:115] op_sel_hi:[1,0,0]
	v_rcp_f32_e32 v168, v168
	v_rcp_f32_e32 v169, v169
	v_pk_mul_f32 v[170:171], v[170:171], s[18:19] op_sel_hi:[1,0]
	v_pk_fma_f32 v[126:127], v[166:167], v[126:127], s[10:11] op_sel_hi:[1,1,0]
	v_exp_f32_e32 v170, v170
	v_exp_f32_e32 v171, v171
	v_pk_fma_f32 v[126:127], v[166:167], v[126:127], s[56:57] op_sel_hi:[1,1,0]
	v_cmp_gt_f32_e32 vcc, 0, v111
	v_pk_fma_f32 v[126:127], v[166:167], v[126:127], s[64:65] op_sel_hi:[1,1,0]
	v_pk_mul_f32 v[120:121], v[170:171], v[120:121]
	v_pk_mul_f32 v[126:127], v[166:167], v[126:127]
	v_pk_fma_f32 v[166:167], v[168:169], s[38:39], v[114:115] op_sel_hi:[1,0,0]
	v_pk_mul_f32 v[170:171], v[162:163], v[162:163]
	v_pk_fma_f32 v[166:167], v[168:169], v[166:167], s[10:11] op_sel_hi:[1,1,0]
	v_pk_mul_f32 v[170:171], v[170:171], s[18:19] op_sel_hi:[1,0]
	v_pk_fma_f32 v[166:167], v[168:169], v[166:167], s[56:57] op_sel_hi:[1,1,0]
	v_exp_f32_e32 v170, v170
	v_pk_fma_f32 v[166:167], v[168:169], v[166:167], s[64:65] op_sel_hi:[1,1,0]
	v_exp_f32_e32 v171, v171
	v_pk_mul_f32 v[166:167], v[168:169], v[166:167]
	v_pk_mul_f32 v[168:169], v[110:111], v[120:121]
	v_pk_fma_f32 v[120:121], v[110:111], v[120:121], v[110:111] neg_lo:[1,0,0] neg_hi:[1,0,0]
	v_pk_fma_f32 v[132:133], v[16:17], v[136:137], v[132:133]
	v_cndmask_b32_e32 v111, v121, v169, vcc
	v_cmp_gt_f32_e32 vcc, 0, v110
	v_pk_fma_f32 v[128:129], v[54:55], v[146:147], v[128:129]
	v_or_b32_e32 v0, 2, v164
	v_cndmask_b32_e32 v110, v120, v168, vcc
	v_pk_mul_f32 v[106:107], v[106:107], v[110:111]
	v_pk_mul_f32 v[110:111], v[170:171], v[126:127]
	v_pk_mul_f32 v[126:127], v[108:109], v[108:109]
	v_pk_mul_f32 v[120:121], v[162:163], v[110:111]
	v_pk_mul_f32 v[126:127], v[126:127], s[18:19] op_sel_hi:[1,0]
	v_pk_fma_f32 v[110:111], v[162:163], v[110:111], v[162:163] neg_lo:[1,0,0] neg_hi:[1,0,0]
	v_cmp_gt_f32_e32 vcc, 0, v163
	v_exp_f32_e32 v126, v126
	v_exp_f32_e32 v127, v127
	v_cndmask_b32_e32 v111, v111, v121, vcc
	v_cmp_gt_f32_e32 vcc, 0, v162
	v_cvt_pk_bf16_f32 v106, v106, v107
	s_nop 0
	v_cndmask_b32_e32 v110, v110, v120, vcc
	v_pk_mul_f32 v[110:111], v[132:133], v[110:111]
	v_cmp_gt_f32_e32 vcc, 0, v109
	v_cvt_pk_bf16_f32 v107, v110, v111
	v_pk_mul_f32 v[110:111], v[126:127], v[166:167]
	v_and_b32_e32 v127, 0x7fffffff, v159
	v_and_b32_e32 v126, 0x7fffffff, v158
	v_pk_fma_f32 v[126:127], v[126:127], s[14:15], 1.0 op_sel_hi:[1,0,0]
	v_pk_mul_f32 v[120:121], v[108:109], v[110:111]
	v_rcp_f32_e32 v126, v126
	v_rcp_f32_e32 v127, v127
	v_pk_fma_f32 v[110:111], v[108:109], v[110:111], v[108:109] neg_lo:[1,0,0] neg_hi:[1,0,0]
	s_waitcnt vmcnt(10)
; __device__ __forceinline__ unsigned cvt_pk_bf16(float lo, float hi) { f32x2 v = {lo, hi}; bf16x2_t b = __builtin_convertvector(v, bf16x2_t); return __builtin_bit_cast(unsigned, b); }
; __device__ __forceinline__ void unpack8(const u32x4& r, float (&v)[8]) { v[0] = bf_lo(r.x); v[1] = bf_hi(r.x); v[2] = bf_lo(r.y); v[3] = bf_hi(r.y); v[4] = bf_lo(r.z); v[5] = bf_hi(r.z); v[6] = bf_lo(r.w); v[7] = bf_hi(r.w); }
; __device__ __forceinline__ f32x2 gelu_pk(f32x2 v) {
;     const f32x2 av = __builtin_elementwise_abs(v), d = av * 0.2316418882f + 1.0f;
;     f32x2 t; t.x = __builtin_amdgcn_rcpf(d.x); t.y = __builtin_amdgcn_rcpf(d.y);
;     f32x2 q = t * 0.5307027145f + (-0.7265760135f); q = q * t + 0.7107068705f; q = q * t + (-0.142248368f); q = q * t + 0.127414796f; q = q * t;
;     const f32x2 s = (v * v) * (-0.72134752044f);
;     f32x2 e; e.x = __builtin_amdgcn_exp2f(s.x); e.y = __builtin_amdgcn_exp2f(s.y);
;     const f32x2 m = v * (q * e), r = v - m;
;     f32x2 o; o.x = v.x < 0.f ? m.x : r.x; o.y = v.y < 0.f ? m.y : r.y; return o;
; }
; __device__ __forceinline__ void conv_phase(KP kp, int l, int a0t, int na) {
;     ...
;             for (int k = 0; k < 3; ++k) { float xa[8], xb[8]; unpack8(ra[i + k], xa); unpack8(rb[i + k], xb);
; #pragma unroll
;                 for (int e = 0; e < 8; ++e) { va[e] += wa[k][e] * xa[e]; vb[e] += wb[k][e] * xb[e]; } }
;             u32x4 o; { f32x2 gg;
;                 gg = gelu_pk((f32x2){va[0], va[1]}); o.x = cvt_pk_bf16(gg.x * vb[0], gg.y * vb[1]); gg = gelu_pk((f32x2){va[2], va[3]}); o.y = cvt_pk_bf16(gg.x * vb[2], gg.y * vb[3]);
;                 gg = gelu_pk((f32x2){va[4], va[5]}); o.z = cvt_pk_bf16(gg.x * vb[4], gg.y * vb[5]); gg = gelu_pk((f32x2){va[6], va[7]}); o.w = cvt_pk_bf16(gg.x * vb[6], gg.y * vb[7]); }
;             *(u32x4*)(ACT + (size_t)(row0 + i) * FF + j) = o;
	v_lshlrev_b32_e32 v132, 16, v101
	v_cndmask_b32_e32 v109, v111, v121, vcc
	v_cmp_gt_f32_e32 vcc, 0, v108
	v_and_b32_e32 v133, 0xffff0000, v101
	s_nop 0
	v_cndmask_b32_e32 v108, v110, v120, vcc
	v_pk_mul_f32 v[120:121], v[158:159], v[158:159]
	v_pk_fma_f32 v[110:111], v[126:127], s[38:39], v[114:115] op_sel_hi:[1,0,0]
	v_pk_mul_f32 v[120:121], v[120:121], s[18:19] op_sel_hi:[1,0]
	v_pk_fma_f32 v[110:111], v[126:127], v[110:111], s[10:11] op_sel_hi:[1,1,0]
	v_exp_f32_e32 v120, v120
	v_exp_f32_e32 v121, v121
	v_pk_fma_f32 v[110:111], v[126:127], v[110:111], s[56:57] op_sel_hi:[1,1,0]
	v_cmp_gt_f32_e32 vcc, 0, v159
	v_pk_fma_f32 v[110:111], v[126:127], v[110:111], s[64:65] op_sel_hi:[1,1,0]
	v_pk_mul_f32 v[108:109], v[128:129], v[108:109]
	v_pk_mul_f32 v[110:111], v[126:127], v[110:111]
	v_cvt_pk_bf16_f32 v108, v108, v109
	v_pk_mul_f32 v[110:111], v[120:121], v[110:111]
	v_lshlrev_b32_e32 v128, 16, v100
	v_pk_mul_f32 v[120:121], v[158:159], v[110:111]
	v_pk_fma_f32 v[110:111], v[158:159], v[110:111], v[158:159] neg_lo:[1,0,0] neg_hi:[1,0,0]
	v_and_b32_e32 v129, 0xffff0000, v100
	v_cndmask_b32_e32 v111, v111, v121, vcc
	v_cmp_gt_f32_e32 vcc, 0, v158
	s_nop 1
	v_cndmask_b32_e32 v110, v110, v120, vcc
	v_pk_mul_f32 v[110:111], v[160:161], v[110:111]
	s_nop 0
	v_cvt_pk_bf16_f32 v109, v110, v111
	v_mad_i64_i32 v[110:111], s[12:13], v0, s2, v[144:145]
	global_store_dwordx4 v[110:111], v[106:109], off
	v_lshlrev_b32_e32 v110, 16, v105
	v_and_b32_e32 v111, 0xffff0000, v105
	v_pk_fma_f32 v[106:107], v[28:29], v[138:139], v[60:61]
	v_pk_fma_f32 v[108:109], v[32:33], v[154:155], v[64:65]
	v_pk_fma_f32 v[106:107], v[36:37], v[122:123], v[106:107]
	v_pk_fma_f32 v[108:109], v[48:49], v[148:149], v[108:109]
	v_pk_fma_f32 v[120:121], v[52:53], v[110:111], v[106:107]
	v_pk_fma_f32 v[138:139], v[56:57], v[132:133], v[108:109]
	v_pk_fma_f32 v[106:107], v[26:27], v[134:135], v[58:59]
	v_pk_fma_f32 v[108:109], v[30:31], v[152:153], v[62:63]
	v_pk_fma_f32 v[106:107], v[34:35], v[118:119], v[106:107]
	v_pk_fma_f32 v[126:127], v[46:47], v[146:147], v[108:109]
	v_lshlrev_b32_e32 v108, 16, v104
	v_and_b32_e32 v109, 0xffff0000, v104
	v_pk_fma_f32 v[100:101], v[50:51], v[108:109], v[106:107]
	v_pk_fma_f32 v[104:105], v[4:5], v[130:131], v[40:41]
	v_pk_fma_f32 v[106:107], v[8:9], v[150:151], v[44:45]
	v_pk_fma_f32 v[104:105], v[12:13], v[116:117], v[104:105]
	v_pk_fma_f32 v[130:131], v[24:25], v[136:137], v[106:107]
	v_lshlrev_b32_e32 v106, 16, v103
	v_and_b32_e32 v107, 0xffff0000, v103
	v_pk_fma_f32 v[150:151], v[20:21], v[106:107], v[104:105]
	v_pk_fma_f32 v[104:105], v[2:3], v[124:125], v[38:39]
	v_pk_fma_f32 v[124:125], v[6:7], v[156:157], v[42:43]
	v_pk_fma_f32 v[152:153], v[10:11], v[112:113], v[104:105]
	v_lshlrev_b32_e32 v104, 16, v102
	v_and_b32_e32 v105, 0xffff0000, v102
	v_pk_fma_f32 v[102:103], v[18:19], v[104:105], v[152:153]
	v_pk_fma_f32 v[154:155], v[22:23], v[140:141], v[124:125]
	v_and_b32_e32 v125, 0x7fffffff, v103
	v_and_b32_e32 v124, 0x7fffffff, v102
	v_pk_fma_f32 v[124:125], v[124:125], s[14:15], 1.0 op_sel_hi:[1,0,0]
	v_and_b32_e32 v157, 0x7fffffff, v151
	v_rcp_f32_e32 v152, v124
	v_rcp_f32_e32 v153, v125
	v_and_b32_e32 v156, 0x7fffffff, v150
	v_lshlrev_b32_e32 v124, 16, v98
	v_and_b32_e32 v125, 0xffff0000, v98
	v_pk_fma_f32 v[156:157], v[156:157], s[14:15], 1.0 op_sel_hi:[1,0,0]
	v_pk_fma_f32 v[134:135], v[54:55], v[128:129], v[126:127]
	v_lshlrev_b32_e32 v126, 16, v99
	v_and_b32_e32 v127, 0xffff0000, v99
	v_pk_fma_f32 v[98:99], v[14:15], v[124:125], v[154:155]
	v_pk_fma_f32 v[154:155], v[152:153], s[38:39], v[114:115] op_sel_hi:[1,0,0]
	v_rcp_f32_e32 v156, v156
	v_rcp_f32_e32 v157, v157
	v_pk_fma_f32 v[154:155], v[152:153], v[154:155], s[10:11] op_sel_hi:[1,1,0]
	v_and_b32_e32 v159, 0x7fffffff, v101
	v_pk_fma_f32 v[154:155], v[152:153], v[154:155], s[56:57] op_sel_hi:[1,1,0]
	v_and_b32_e32 v158, 0x7fffffff, v100
	v_pk_fma_f32 v[154:155], v[152:153], v[154:155], s[64:65] op_sel_hi:[1,1,0]
	v_pk_fma_f32 v[158:159], v[158:159], s[14:15], 1.0 op_sel_hi:[1,0,0]
	v_pk_mul_f32 v[160:161], v[102:103], v[102:103]
	v_pk_mul_f32 v[152:153], v[152:153], v[154:155]
	v_pk_fma_f32 v[154:155], v[156:157], s[38:39], v[114:115] op_sel_hi:[1,0,0]
	v_rcp_f32_e32 v158, v158
	v_rcp_f32_e32 v159, v159
	v_pk_mul_f32 v[160:161], v[160:161], s[18:19] op_sel_hi:[1,0]
	v_pk_fma_f32 v[154:155], v[156:157], v[154:155], s[10:11] op_sel_hi:[1,1,0]
	v_exp_f32_e32 v160, v160
	v_exp_f32_e32 v161, v161
	v_pk_fma_f32 v[154:155], v[156:157], v[154:155], s[56:57] op_sel_hi:[1,1,0]
	v_cmp_gt_f32_e32 vcc, 0, v103
	v_pk_fma_f32 v[154:155], v[156:157], v[154:155], s[64:65] op_sel_hi:[1,1,0]
	v_pk_mul_f32 v[152:153], v[160:161], v[152:153]
	v_pk_mul_f32 v[154:155], v[156:157], v[154:155]
	v_pk_fma_f32 v[156:157], v[158:159], s[38:39], v[114:115] op_sel_hi:[1,0,0]
	v_pk_mul_f32 v[160:161], v[150:151], v[150:151]
	v_pk_fma_f32 v[156:157], v[158:159], v[156:157], s[10:11] op_sel_hi:[1,1,0]
	v_pk_mul_f32 v[160:161], v[160:161], s[18:19] op_sel_hi:[1,0]
	v_pk_fma_f32 v[156:157], v[158:159], v[156:157], s[56:57] op_sel_hi:[1,1,0]
	v_exp_f32_e32 v160, v160
	v_pk_fma_f32 v[156:157], v[158:159], v[156:157], s[64:65] op_sel_hi:[1,1,0]
	v_exp_f32_e32 v161, v161
	v_pk_mul_f32 v[156:157], v[158:159], v[156:157]
	v_pk_mul_f32 v[158:159], v[102:103], v[152:153]
	v_pk_fma_f32 v[152:153], v[102:103], v[152:153], v[102:103] neg_lo:[1,0,0] neg_hi:[1,0,0]
	v_pk_fma_f32 v[130:131], v[16:17], v[126:127], v[130:131]
	v_cndmask_b32_e32 v103, v153, v159, vcc
	v_cmp_gt_f32_e32 vcc, 0, v102
	v_or_b32_e32 v0, 3, v164
	s_nop 0
	v_cndmask_b32_e32 v102, v152, v158, vcc
	v_pk_mul_f32 v[98:99], v[98:99], v[102:103]
; __device__ __forceinline__ unsigned cvt_pk_bf16(float lo, float hi) { f32x2 v = {lo, hi}; bf16x2_t b = __builtin_convertvector(v, bf16x2_t); return __builtin_bit_cast(unsigned, b); }
; __device__ __forceinline__ void unpack8(const u32x4& r, float (&v)[8]) { v[0] = bf_lo(r.x); v[1] = bf_hi(r.x); v[2] = bf_lo(r.y); v[3] = bf_hi(r.y); v[4] = bf_lo(r.z); v[5] = bf_hi(r.z); v[6] = bf_lo(r.w); v[7] = bf_hi(r.w); }
; __device__ __forceinline__ f32x2 gelu_pk(f32x2 v) {
;     const f32x2 av = __builtin_elementwise_abs(v), d = av * 0.2316418882f + 1.0f;
;     f32x2 t; t.x = __builtin_amdgcn_rcpf(d.x); t.y = __builtin_amdgcn_rcpf(d.y);
;     f32x2 q = t * 0.5307027145f + (-0.7265760135f); q = q * t + 0.7107068705f; q = q * t + (-0.142248368f); q = q * t + 0.127414796f; q = q * t;
;     const f32x2 s = (v * v) * (-0.72134752044f);
;     f32x2 e; e.x = __builtin_amdgcn_exp2f(s.x); e.y = __builtin_amdgcn_exp2f(s.y);
;     const f32x2 m = v * (q * e), r = v - m;
;     f32x2 o; o.x = v.x < 0.f ? m.x : r.x; o.y = v.y < 0.f ? m.y : r.y; return o;
; }
; __device__ __forceinline__ void conv_phase(KP kp, int l, int a0t, int na) {
;     ...
;             for (int k = 0; k < 3; ++k) { float xa[8], xb[8]; unpack8(ra[i + k], xa); unpack8(rb[i + k], xb);
; #pragma unroll
;                 for (int e = 0; e < 8; ++e) { va[e] += wa[k][e] * xa[e]; vb[e] += wb[k][e] * xb[e]; } }
;             u32x4 o; { f32x2 gg;
;                 gg = gelu_pk((f32x2){va[0], va[1]}); o.x = cvt_pk_bf16(gg.x * vb[0], gg.y * vb[1]); gg = gelu_pk((f32x2){va[2], va[3]}); o.y = cvt_pk_bf16(gg.x * vb[2], gg.y * vb[3]);
;                 gg = gelu_pk((f32x2){va[4], va[5]}); o.z = cvt_pk_bf16(gg.x * vb[4], gg.y * vb[5]); gg = gelu_pk((f32x2){va[6], va[7]}); o.w = cvt_pk_bf16(gg.x * vb[6], gg.y * vb[7]); }
;             *(u32x4*)(ACT + (size_t)(row0 + i) * FF + j) = o;
	v_pk_mul_f32 v[102:103], v[160:161], v[154:155]
	v_pk_mul_f32 v[154:155], v[100:101], v[100:101]
	v_pk_mul_f32 v[152:153], v[150:151], v[102:103]
	v_pk_mul_f32 v[154:155], v[154:155], s[18:19] op_sel_hi:[1,0]
	v_pk_fma_f32 v[102:103], v[150:151], v[102:103], v[150:151] neg_lo:[1,0,0] neg_hi:[1,0,0]
	v_cmp_gt_f32_e32 vcc, 0, v151
	v_exp_f32_e32 v154, v154
	v_exp_f32_e32 v155, v155
	v_cndmask_b32_e32 v103, v103, v153, vcc
	v_cmp_gt_f32_e32 vcc, 0, v150
	v_and_b32_e32 v151, 0x7fffffff, v121
	v_and_b32_e32 v150, 0x7fffffff, v120
	v_cndmask_b32_e32 v102, v102, v152, vcc
	v_pk_mul_f32 v[102:103], v[130:131], v[102:103]
	v_pk_fma_f32 v[150:151], v[150:151], s[14:15], 1.0 op_sel_hi:[1,0,0]
	v_cvt_pk_bf16_f32 v98, v98, v99
	v_cvt_pk_bf16_f32 v99, v102, v103
	v_pk_mul_f32 v[102:103], v[154:155], v[156:157]
	v_rcp_f32_e32 v150, v150
	v_rcp_f32_e32 v151, v151
	v_pk_mul_f32 v[130:131], v[100:101], v[102:103]
	v_pk_fma_f32 v[102:103], v[100:101], v[102:103], v[100:101] neg_lo:[1,0,0] neg_hi:[1,0,0]
	v_cmp_gt_f32_e32 vcc, 0, v101
	s_nop 1
	v_cndmask_b32_e32 v101, v103, v131, vcc
	v_cmp_gt_f32_e32 vcc, 0, v100
	s_nop 1
	v_cndmask_b32_e32 v100, v102, v130, vcc
	v_pk_mul_f32 v[130:131], v[120:121], v[120:121]
	v_pk_fma_f32 v[102:103], v[150:151], s[38:39], v[114:115] op_sel_hi:[1,0,0]
	v_pk_mul_f32 v[130:131], v[130:131], s[18:19] op_sel_hi:[1,0]
	v_pk_fma_f32 v[102:103], v[150:151], v[102:103], s[10:11] op_sel_hi:[1,1,0]
	v_exp_f32_e32 v130, v130
	v_exp_f32_e32 v131, v131
	v_pk_fma_f32 v[102:103], v[150:151], v[102:103], s[56:57] op_sel_hi:[1,1,0]
	v_cmp_gt_f32_e32 vcc, 0, v121
	v_pk_fma_f32 v[102:103], v[150:151], v[102:103], s[64:65] op_sel_hi:[1,1,0]
	v_pk_mul_f32 v[100:101], v[134:135], v[100:101]
	v_pk_mul_f32 v[102:103], v[150:151], v[102:103]
	v_cvt_pk_bf16_f32 v100, v100, v101
	v_pk_mul_f32 v[102:103], v[130:131], v[102:103]
	s_nop 0
	v_pk_mul_f32 v[130:131], v[120:121], v[102:103]
	v_pk_fma_f32 v[102:103], v[120:121], v[102:103], v[120:121] neg_lo:[1,0,0] neg_hi:[1,0,0]
	s_waitcnt vmcnt(9)
	v_and_b32_e32 v121, 0xffff0000, v93
	v_cndmask_b32_e32 v103, v103, v131, vcc
	v_cmp_gt_f32_e32 vcc, 0, v120
	v_lshlrev_b32_e32 v120, 16, v93
	s_nop 0
	v_cndmask_b32_e32 v102, v102, v130, vcc
	v_pk_mul_f32 v[102:103], v[138:139], v[102:103]
	s_nop 0
	v_cvt_pk_bf16_f32 v101, v102, v103
	v_mad_i64_i32 v[102:103], s[12:13], v0, s2, v[144:145]
	global_store_dwordx4 v[102:103], v[98:101], off
	v_lshlrev_b32_e32 v102, 16, v97
	v_and_b32_e32 v103, 0xffff0000, v97
	v_pk_fma_f32 v[98:99], v[28:29], v[122:123], v[60:61]
	v_pk_fma_f32 v[100:101], v[32:33], v[148:149], v[64:65]
	v_pk_fma_f32 v[98:99], v[36:37], v[110:111], v[98:99]
	v_pk_fma_f32 v[100:101], v[48:49], v[132:133], v[100:101]
	v_pk_fma_f32 v[122:123], v[52:53], v[102:103], v[98:99]
	v_pk_fma_f32 v[130:131], v[56:57], v[120:121], v[100:101]
	v_pk_fma_f32 v[98:99], v[26:27], v[118:119], v[58:59]
	v_pk_fma_f32 v[100:101], v[30:31], v[146:147], v[62:63]
	v_pk_fma_f32 v[98:99], v[34:35], v[108:109], v[98:99]
	v_pk_fma_f32 v[134:135], v[46:47], v[128:129], v[100:101]
	v_lshlrev_b32_e32 v100, 16, v96
	v_and_b32_e32 v101, 0xffff0000, v96
	v_lshlrev_b32_e32 v118, 16, v92
	v_and_b32_e32 v119, 0xffff0000, v92
	v_pk_fma_f32 v[92:93], v[50:51], v[100:101], v[98:99]
	v_pk_fma_f32 v[96:97], v[4:5], v[116:117], v[40:41]
	v_pk_fma_f32 v[98:99], v[8:9], v[136:137], v[44:45]
	v_pk_fma_f32 v[96:97], v[12:13], v[106:107], v[96:97]
	v_pk_fma_f32 v[136:137], v[24:25], v[126:127], v[98:99]
	v_lshlrev_b32_e32 v98, 16, v95
	v_and_b32_e32 v99, 0xffff0000, v95
	v_pk_fma_f32 v[138:139], v[20:21], v[98:99], v[96:97]
	v_pk_fma_f32 v[96:97], v[2:3], v[112:113], v[38:39]
	v_pk_fma_f32 v[112:113], v[6:7], v[140:141], v[42:43]
	v_pk_fma_f32 v[140:141], v[10:11], v[104:105], v[96:97]
	v_lshlrev_b32_e32 v96, 16, v94
	v_and_b32_e32 v97, 0xffff0000, v94
	v_pk_fma_f32 v[94:95], v[18:19], v[96:97], v[140:141]
	v_pk_fma_f32 v[146:147], v[22:23], v[124:125], v[112:113]
	v_and_b32_e32 v113, 0x7fffffff, v95
	v_and_b32_e32 v112, 0x7fffffff, v94
	v_pk_fma_f32 v[112:113], v[112:113], s[14:15], 1.0 op_sel_hi:[1,0,0]
	v_and_b32_e32 v149, 0x7fffffff, v139
	v_rcp_f32_e32 v140, v112
	v_rcp_f32_e32 v141, v113
	v_and_b32_e32 v148, 0x7fffffff, v138
	v_lshlrev_b32_e32 v112, 16, v90
	v_and_b32_e32 v113, 0xffff0000, v90
	v_pk_fma_f32 v[148:149], v[148:149], s[14:15], 1.0 op_sel_hi:[1,0,0]
	v_lshlrev_b32_e32 v116, 16, v91
	v_and_b32_e32 v117, 0xffff0000, v91
	v_pk_fma_f32 v[90:91], v[14:15], v[112:113], v[146:147]
	v_pk_fma_f32 v[146:147], v[140:141], s[38:39], v[114:115] op_sel_hi:[1,0,0]
	v_rcp_f32_e32 v148, v148
	v_rcp_f32_e32 v149, v149
	v_pk_fma_f32 v[146:147], v[140:141], v[146:147], s[10:11] op_sel_hi:[1,1,0]
	v_and_b32_e32 v151, 0x7fffffff, v93
	v_pk_fma_f32 v[146:147], v[140:141], v[146:147], s[56:57] op_sel_hi:[1,1,0]
	v_and_b32_e32 v150, 0x7fffffff, v92
	v_pk_fma_f32 v[146:147], v[140:141], v[146:147], s[64:65] op_sel_hi:[1,1,0]
	v_pk_fma_f32 v[150:151], v[150:151], s[14:15], 1.0 op_sel_hi:[1,0,0]
	v_pk_mul_f32 v[152:153], v[94:95], v[94:95]
	v_pk_mul_f32 v[140:141], v[140:141], v[146:147]
	v_pk_fma_f32 v[146:147], v[148:149], s[38:39], v[114:115] op_sel_hi:[1,0,0]
	v_rcp_f32_e32 v150, v150
	v_rcp_f32_e32 v151, v151
	v_pk_mul_f32 v[152:153], v[152:153], s[18:19] op_sel_hi:[1,0]
	v_pk_fma_f32 v[146:147], v[148:149], v[146:147], s[10:11] op_sel_hi:[1,1,0]
	v_exp_f32_e32 v152, v152
	v_exp_f32_e32 v153, v153
	v_pk_fma_f32 v[146:147], v[148:149], v[146:147], s[56:57] op_sel_hi:[1,1,0]
	v_cmp_gt_f32_e32 vcc, 0, v95
	v_pk_fma_f32 v[146:147], v[148:149], v[146:147], s[64:65] op_sel_hi:[1,1,0]
	v_pk_mul_f32 v[140:141], v[152:153], v[140:141]
; __device__ __forceinline__ unsigned cvt_pk_bf16(float lo, float hi) { f32x2 v = {lo, hi}; bf16x2_t b = __builtin_convertvector(v, bf16x2_t); return __builtin_bit_cast(unsigned, b); }
; __device__ __forceinline__ void unpack8(const u32x4& r, float (&v)[8]) { v[0] = bf_lo(r.x); v[1] = bf_hi(r.x); v[2] = bf_lo(r.y); v[3] = bf_hi(r.y); v[4] = bf_lo(r.z); v[5] = bf_hi(r.z); v[6] = bf_lo(r.w); v[7] = bf_hi(r.w); }
; __device__ __forceinline__ f32x2 gelu_pk(f32x2 v) {
;     const f32x2 av = __builtin_elementwise_abs(v), d = av * 0.2316418882f + 1.0f;
;     f32x2 t; t.x = __builtin_amdgcn_rcpf(d.x); t.y = __builtin_amdgcn_rcpf(d.y);
;     f32x2 q = t * 0.5307027145f + (-0.7265760135f); q = q * t + 0.7107068705f; q = q * t + (-0.142248368f); q = q * t + 0.127414796f; q = q * t;
;     const f32x2 s = (v * v) * (-0.72134752044f);
;     f32x2 e; e.x = __builtin_amdgcn_exp2f(s.x); e.y = __builtin_amdgcn_exp2f(s.y);
;     const f32x2 m = v * (q * e), r = v - m;
;     f32x2 o; o.x = v.x < 0.f ? m.x : r.x; o.y = v.y < 0.f ? m.y : r.y; return o;
; }
; __device__ __forceinline__ void conv_phase(KP kp, int l, int a0t, int na) {
;     ...
;             for (int k = 0; k < 3; ++k) { float xa[8], xb[8]; unpack8(ra[i + k], xa); unpack8(rb[i + k], xb);
; #pragma unroll
;                 for (int e = 0; e < 8; ++e) { va[e] += wa[k][e] * xa[e]; vb[e] += wb[k][e] * xb[e]; } }
;             u32x4 o; { f32x2 gg;
;                 gg = gelu_pk((f32x2){va[0], va[1]}); o.x = cvt_pk_bf16(gg.x * vb[0], gg.y * vb[1]); gg = gelu_pk((f32x2){va[2], va[3]}); o.y = cvt_pk_bf16(gg.x * vb[2], gg.y * vb[3]);
;                 gg = gelu_pk((f32x2){va[4], va[5]}); o.z = cvt_pk_bf16(gg.x * vb[4], gg.y * vb[5]); gg = gelu_pk((f32x2){va[6], va[7]}); o.w = cvt_pk_bf16(gg.x * vb[6], gg.y * vb[7]); }
;             *(u32x4*)(ACT + (size_t)(row0 + i) * FF + j) = o;
	v_pk_mul_f32 v[146:147], v[148:149], v[146:147]
	v_pk_fma_f32 v[148:149], v[150:151], s[38:39], v[114:115] op_sel_hi:[1,0,0]
	v_pk_mul_f32 v[152:153], v[138:139], v[138:139]
	v_pk_fma_f32 v[148:149], v[150:151], v[148:149], s[10:11] op_sel_hi:[1,1,0]
	v_pk_mul_f32 v[152:153], v[152:153], s[18:19] op_sel_hi:[1,0]
	v_pk_fma_f32 v[148:149], v[150:151], v[148:149], s[56:57] op_sel_hi:[1,1,0]
	v_exp_f32_e32 v152, v152
	v_pk_fma_f32 v[148:149], v[150:151], v[148:149], s[64:65] op_sel_hi:[1,1,0]
	v_exp_f32_e32 v153, v153
	v_pk_mul_f32 v[148:149], v[150:151], v[148:149]
	v_pk_mul_f32 v[150:151], v[94:95], v[140:141]
	v_pk_fma_f32 v[140:141], v[94:95], v[140:141], v[94:95] neg_lo:[1,0,0] neg_hi:[1,0,0]
	v_pk_fma_f32 v[136:137], v[16:17], v[116:117], v[136:137]
	v_cndmask_b32_e32 v95, v141, v151, vcc
	v_cmp_gt_f32_e32 vcc, 0, v94
	v_pk_fma_f32 v[134:135], v[54:55], v[118:119], v[134:135]
	v_or_b32_e32 v0, 4, v164
	v_cndmask_b32_e32 v94, v140, v150, vcc
	v_pk_mul_f32 v[90:91], v[90:91], v[94:95]
	v_pk_mul_f32 v[94:95], v[152:153], v[146:147]
	v_pk_mul_f32 v[146:147], v[92:93], v[92:93]
	v_pk_mul_f32 v[140:141], v[138:139], v[94:95]
	v_pk_mul_f32 v[146:147], v[146:147], s[18:19] op_sel_hi:[1,0]
	v_pk_fma_f32 v[94:95], v[138:139], v[94:95], v[138:139] neg_lo:[1,0,0] neg_hi:[1,0,0]
	v_cmp_gt_f32_e32 vcc, 0, v139
	v_exp_f32_e32 v146, v146
	v_exp_f32_e32 v147, v147
	v_cndmask_b32_e32 v95, v95, v141, vcc
	v_cmp_gt_f32_e32 vcc, 0, v138
	v_and_b32_e32 v139, 0x7fffffff, v123
	v_and_b32_e32 v138, 0x7fffffff, v122
	v_cndmask_b32_e32 v94, v94, v140, vcc
	v_pk_mul_f32 v[94:95], v[136:137], v[94:95]
	v_cvt_pk_bf16_f32 v90, v90, v91
	v_cvt_pk_bf16_f32 v91, v94, v95
	v_pk_mul_f32 v[94:95], v[146:147], v[148:149]
	v_pk_fma_f32 v[138:139], v[138:139], s[14:15], 1.0 op_sel_hi:[1,0,0]
	v_pk_mul_f32 v[136:137], v[92:93], v[94:95]
	v_pk_fma_f32 v[94:95], v[92:93], v[94:95], v[92:93] neg_lo:[1,0,0] neg_hi:[1,0,0]
	v_cmp_gt_f32_e32 vcc, 0, v93
	v_rcp_f32_e32 v138, v138
	v_rcp_f32_e32 v139, v139
	v_cndmask_b32_e32 v93, v95, v137, vcc
	v_cmp_gt_f32_e32 vcc, 0, v92
	s_nop 1
	v_cndmask_b32_e32 v92, v94, v136, vcc
	v_pk_mul_f32 v[92:93], v[134:135], v[92:93]
	v_pk_mul_f32 v[134:135], v[122:123], v[122:123]
	v_pk_fma_f32 v[94:95], v[138:139], s[38:39], v[114:115] op_sel_hi:[1,0,0]
	v_pk_mul_f32 v[134:135], v[134:135], s[18:19] op_sel_hi:[1,0]
	v_pk_fma_f32 v[94:95], v[138:139], v[94:95], s[10:11] op_sel_hi:[1,1,0]
	v_exp_f32_e32 v134, v134
	v_exp_f32_e32 v135, v135
	v_pk_fma_f32 v[94:95], v[138:139], v[94:95], s[56:57] op_sel_hi:[1,1,0]
	v_cmp_gt_f32_e32 vcc, 0, v123
	v_pk_fma_f32 v[94:95], v[138:139], v[94:95], s[64:65] op_sel_hi:[1,1,0]
	v_cvt_pk_bf16_f32 v92, v92, v93
	v_pk_mul_f32 v[94:95], v[138:139], v[94:95]
	s_nop 0
	v_pk_mul_f32 v[94:95], v[134:135], v[94:95]
	s_nop 0
	v_pk_mul_f32 v[134:135], v[122:123], v[94:95]
	v_pk_fma_f32 v[94:95], v[122:123], v[94:95], v[122:123] neg_lo:[1,0,0] neg_hi:[1,0,0]
	s_nop 0
	v_cndmask_b32_e32 v95, v95, v135, vcc
	v_cmp_gt_f32_e32 vcc, 0, v122
	s_nop 1
	v_cndmask_b32_e32 v94, v94, v134, vcc
	v_pk_mul_f32 v[94:95], v[130:131], v[94:95]
	s_nop 0
	v_cvt_pk_bf16_f32 v93, v94, v95
	v_mad_i64_i32 v[94:95], s[12:13], v0, s2, v[144:145]
	global_store_dwordx4 v[94:95], v[90:93], off
	v_or_b32_e32 v0, 5, v164
	s_nop 0
	v_pk_fma_f32 v[90:91], v[28:29], v[110:111], v[60:61]
	v_pk_fma_f32 v[92:93], v[32:33], v[132:133], v[64:65]
	v_pk_fma_f32 v[90:91], v[36:37], v[102:103], v[90:91]
	v_pk_fma_f32 v[94:95], v[48:49], v[120:121], v[92:93]
	s_waitcnt vmcnt(10)
	v_lshlrev_b32_e32 v92, 16, v89
	v_and_b32_e32 v93, 0xffff0000, v89
	s_waitcnt vmcnt(9)
	v_lshlrev_b32_e32 v110, 16, v85
	v_and_b32_e32 v111, 0xffff0000, v85
	v_pk_fma_f32 v[122:123], v[52:53], v[92:93], v[90:91]
	v_pk_fma_f32 v[90:91], v[26:27], v[108:109], v[58:59]
	v_pk_fma_f32 v[130:131], v[56:57], v[110:111], v[94:95]
	v_pk_fma_f32 v[94:95], v[30:31], v[128:129], v[62:63]
	v_pk_fma_f32 v[128:129], v[34:35], v[100:101], v[90:91]
	v_lshlrev_b32_e32 v90, 16, v88
	v_and_b32_e32 v91, 0xffff0000, v88
	v_lshlrev_b32_e32 v108, 16, v84
	v_and_b32_e32 v109, 0xffff0000, v84
	v_pk_fma_f32 v[84:85], v[4:5], v[106:107], v[40:41]
	v_pk_fma_f32 v[88:89], v[8:9], v[126:127], v[44:45]
	v_pk_fma_f32 v[84:85], v[12:13], v[98:99], v[84:85]
	v_pk_fma_f32 v[106:107], v[24:25], v[116:117], v[88:89]
	v_lshlrev_b32_e32 v88, 16, v87
	v_and_b32_e32 v89, 0xffff0000, v87
	v_pk_fma_f32 v[126:127], v[20:21], v[88:89], v[84:85]
	v_pk_fma_f32 v[84:85], v[2:3], v[104:105], v[38:39]
	v_pk_fma_f32 v[104:105], v[6:7], v[124:125], v[42:43]
	v_pk_fma_f32 v[124:125], v[10:11], v[96:97], v[84:85]
	v_lshlrev_b32_e32 v84, 16, v86
	v_and_b32_e32 v85, 0xffff0000, v86
	v_pk_fma_f32 v[124:125], v[18:19], v[84:85], v[124:125]
	v_and_b32_e32 v137, 0x7fffffff, v127
	v_and_b32_e32 v87, 0x7fffffff, v125
	v_and_b32_e32 v86, 0x7fffffff, v124
	v_pk_fma_f32 v[86:87], v[86:87], s[14:15], 1.0 op_sel_hi:[1,0,0]
	v_and_b32_e32 v136, 0x7fffffff, v126
	v_rcp_f32_e32 v134, v86
	v_rcp_f32_e32 v135, v87
	v_pk_fma_f32 v[94:95], v[46:47], v[118:119], v[94:95]
	v_pk_fma_f32 v[104:105], v[22:23], v[112:113], v[104:105]
	v_lshlrev_b32_e32 v86, 16, v82
	v_and_b32_e32 v87, 0xffff0000, v82
	v_pk_fma_f32 v[136:137], v[136:137], s[14:15], 1.0 op_sel_hi:[1,0,0]
	v_pk_fma_f32 v[132:133], v[54:55], v[108:109], v[94:95]
	v_lshlrev_b32_e32 v94, 16, v83
	v_and_b32_e32 v95, 0xffff0000, v83
	v_pk_fma_f32 v[82:83], v[14:15], v[86:87], v[104:105]
	v_pk_fma_f32 v[104:105], v[134:135], s[38:39], v[114:115] op_sel_hi:[1,0,0]
	v_rcp_f32_e32 v136, v136
	v_rcp_f32_e32 v137, v137
	v_pk_fma_f32 v[128:129], v[50:51], v[90:91], v[128:129]
	v_pk_fma_f32 v[104:105], v[134:135], v[104:105], s[10:11] op_sel_hi:[1,1,0]
; __device__ __forceinline__ unsigned cvt_pk_bf16(float lo, float hi) { f32x2 v = {lo, hi}; bf16x2_t b = __builtin_convertvector(v, bf16x2_t); return __builtin_bit_cast(unsigned, b); }
; __device__ __forceinline__ void unpack8(const u32x4& r, float (&v)[8]) { v[0] = bf_lo(r.x); v[1] = bf_hi(r.x); v[2] = bf_lo(r.y); v[3] = bf_hi(r.y); v[4] = bf_lo(r.z); v[5] = bf_hi(r.z); v[6] = bf_lo(r.w); v[7] = bf_hi(r.w); }
; __device__ __forceinline__ f32x2 gelu_pk(f32x2 v) {
;     const f32x2 av = __builtin_elementwise_abs(v), d = av * 0.2316418882f + 1.0f;
;     f32x2 t; t.x = __builtin_amdgcn_rcpf(d.x); t.y = __builtin_amdgcn_rcpf(d.y);
;     f32x2 q = t * 0.5307027145f + (-0.7265760135f); q = q * t + 0.7107068705f; q = q * t + (-0.142248368f); q = q * t + 0.127414796f; q = q * t;
;     const f32x2 s = (v * v) * (-0.72134752044f);
;     f32x2 e; e.x = __builtin_amdgcn_exp2f(s.x); e.y = __builtin_amdgcn_exp2f(s.y);
;     const f32x2 m = v * (q * e), r = v - m;
;     f32x2 o; o.x = v.x < 0.f ? m.x : r.x; o.y = v.y < 0.f ? m.y : r.y; return o;
; }
; __device__ __forceinline__ void conv_phase(KP kp, int l, int a0t, int na) {
;     ...
;             for (int k = 0; k < 3; ++k) { float xa[8], xb[8]; unpack8(ra[i + k], xa); unpack8(rb[i + k], xb);
; #pragma unroll
;                 for (int e = 0; e < 8; ++e) { va[e] += wa[k][e] * xa[e]; vb[e] += wb[k][e] * xb[e]; } }
;             u32x4 o; { f32x2 gg;
;                 gg = gelu_pk((f32x2){va[0], va[1]}); o.x = cvt_pk_bf16(gg.x * vb[0], gg.y * vb[1]); gg = gelu_pk((f32x2){va[2], va[3]}); o.y = cvt_pk_bf16(gg.x * vb[2], gg.y * vb[3]);
;                 gg = gelu_pk((f32x2){va[4], va[5]}); o.z = cvt_pk_bf16(gg.x * vb[4], gg.y * vb[5]); gg = gelu_pk((f32x2){va[6], va[7]}); o.w = cvt_pk_bf16(gg.x * vb[6], gg.y * vb[7]); }
;             *(u32x4*)(ACT + (size_t)(row0 + i) * FF + j) = o;
	v_and_b32_e32 v139, 0x7fffffff, v129
	v_pk_fma_f32 v[104:105], v[134:135], v[104:105], s[56:57] op_sel_hi:[1,1,0]
	v_and_b32_e32 v138, 0x7fffffff, v128
	v_pk_fma_f32 v[104:105], v[134:135], v[104:105], s[64:65] op_sel_hi:[1,1,0]
	v_pk_fma_f32 v[138:139], v[138:139], s[14:15], 1.0 op_sel_hi:[1,0,0]
	v_pk_mul_f32 v[104:105], v[134:135], v[104:105]
	v_pk_fma_f32 v[134:135], v[136:137], s[38:39], v[114:115] op_sel_hi:[1,0,0]
	v_rcp_f32_e32 v138, v138
	v_rcp_f32_e32 v139, v139
	v_pk_mul_f32 v[140:141], v[124:125], v[124:125]
	v_pk_fma_f32 v[134:135], v[136:137], v[134:135], s[10:11] op_sel_hi:[1,1,0]
	v_pk_mul_f32 v[140:141], v[140:141], s[18:19] op_sel_hi:[1,0]
	v_pk_fma_f32 v[134:135], v[136:137], v[134:135], s[56:57] op_sel_hi:[1,1,0]
	v_exp_f32_e32 v140, v140
	v_exp_f32_e32 v141, v141
	v_pk_fma_f32 v[134:135], v[136:137], v[134:135], s[64:65] op_sel_hi:[1,1,0]
	v_cmp_gt_f32_e32 vcc, 0, v125
	v_pk_mul_f32 v[134:135], v[136:137], v[134:135]
	v_pk_fma_f32 v[136:137], v[138:139], s[38:39], v[114:115] op_sel_hi:[1,0,0]
	v_pk_mul_f32 v[104:105], v[140:141], v[104:105]
	v_pk_fma_f32 v[136:137], v[138:139], v[136:137], s[10:11] op_sel_hi:[1,1,0]
	v_pk_mul_f32 v[140:141], v[126:127], v[126:127]
	v_pk_fma_f32 v[136:137], v[138:139], v[136:137], s[56:57] op_sel_hi:[1,1,0]
	v_pk_mul_f32 v[140:141], v[140:141], s[18:19] op_sel_hi:[1,0]
	v_pk_fma_f32 v[136:137], v[138:139], v[136:137], s[64:65] op_sel_hi:[1,1,0]
	v_exp_f32_e32 v140, v140
	v_pk_mul_f32 v[136:137], v[138:139], v[136:137]
	v_pk_mul_f32 v[138:139], v[124:125], v[104:105]
	v_pk_fma_f32 v[104:105], v[124:125], v[104:105], v[124:125] neg_lo:[1,0,0] neg_hi:[1,0,0]
	v_exp_f32_e32 v141, v141
	v_cndmask_b32_e32 v105, v105, v139, vcc
	v_cmp_gt_f32_e32 vcc, 0, v124
	v_pk_fma_f32 v[106:107], v[16:17], v[94:95], v[106:107]
	v_pk_fma_f32 v[100:101], v[26:27], v[100:101], v[58:59]
	v_cndmask_b32_e32 v104, v104, v138, vcc
	v_pk_mul_f32 v[82:83], v[82:83], v[104:105]
	v_cmp_gt_f32_e32 vcc, 0, v127
	v_cvt_pk_bf16_f32 v104, v82, v83
	v_pk_mul_f32 v[82:83], v[140:141], v[134:135]
	v_pk_mul_f32 v[134:135], v[128:129], v[128:129]
	v_pk_mul_f32 v[124:125], v[126:127], v[82:83]
	v_pk_mul_f32 v[134:135], v[134:135], s[18:19] op_sel_hi:[1,0]
	v_pk_fma_f32 v[82:83], v[126:127], v[82:83], v[126:127] neg_lo:[1,0,0] neg_hi:[1,0,0]
	v_exp_f32_e32 v134, v134
	v_exp_f32_e32 v135, v135
	v_cndmask_b32_e32 v83, v83, v125, vcc
	v_cmp_gt_f32_e32 vcc, 0, v126
	v_and_b32_e32 v125, 0x7fffffff, v123
	v_pk_mul_f32 v[126:127], v[122:123], v[122:123]
	v_cndmask_b32_e32 v82, v82, v124, vcc
	v_pk_mul_f32 v[82:83], v[106:107], v[82:83]
	v_and_b32_e32 v124, 0x7fffffff, v122
	v_cvt_pk_bf16_f32 v105, v82, v83
	v_pk_mul_f32 v[82:83], v[134:135], v[136:137]
	v_pk_fma_f32 v[124:125], v[124:125], s[14:15], 1.0 op_sel_hi:[1,0,0]
	v_pk_mul_f32 v[106:107], v[128:129], v[82:83]
	v_pk_fma_f32 v[82:83], v[128:129], v[82:83], v[128:129] neg_lo:[1,0,0] neg_hi:[1,0,0]
	v_cmp_gt_f32_e32 vcc, 0, v129
	v_rcp_f32_e32 v124, v124
	v_rcp_f32_e32 v125, v125
	v_cndmask_b32_e32 v83, v83, v107, vcc
	v_cmp_gt_f32_e32 vcc, 0, v128
	v_pk_mul_f32 v[126:127], v[126:127], s[18:19] op_sel_hi:[1,0]
	v_pk_fma_f32 v[118:119], v[30:31], v[118:119], v[62:63]
	v_cndmask_b32_e32 v82, v82, v106, vcc
	v_pk_mul_f32 v[82:83], v[132:133], v[82:83]
	v_exp_f32_e32 v126, v126
	v_cvt_pk_bf16_f32 v106, v82, v83
	v_pk_fma_f32 v[82:83], v[124:125], s[38:39], v[114:115] op_sel_hi:[1,0,0]
	v_exp_f32_e32 v127, v127
	v_pk_fma_f32 v[82:83], v[124:125], v[82:83], s[10:11] op_sel_hi:[1,1,0]
	v_cmp_gt_f32_e32 vcc, 0, v123
	v_pk_fma_f32 v[82:83], v[124:125], v[82:83], s[56:57] op_sel_hi:[1,1,0]
	v_pk_fma_f32 v[96:97], v[2:3], v[96:97], v[38:39]
	v_pk_fma_f32 v[82:83], v[124:125], v[82:83], s[64:65] op_sel_hi:[1,1,0]
	v_pk_fma_f32 v[100:101], v[34:35], v[90:91], v[100:101]
	v_pk_mul_f32 v[82:83], v[124:125], v[82:83]
	v_pk_fma_f32 v[118:119], v[46:47], v[108:109], v[118:119]
	v_pk_mul_f32 v[82:83], v[126:127], v[82:83]
	v_pk_fma_f32 v[96:97], v[10:11], v[84:85], v[96:97]
	v_pk_mul_f32 v[124:125], v[122:123], v[82:83]
	v_pk_fma_f32 v[82:83], v[122:123], v[82:83], v[122:123] neg_lo:[1,0,0] neg_hi:[1,0,0]
	v_pk_fma_f32 v[98:99], v[4:5], v[98:99], v[40:41]
	v_cndmask_b32_e32 v83, v83, v125, vcc
	v_cmp_gt_f32_e32 vcc, 0, v122
	s_waitcnt vmcnt(8)
	v_and_b32_e32 v125, 0xffff0000, v78
	v_pk_fma_f32 v[98:99], v[12:13], v[88:89], v[98:99]
	v_cndmask_b32_e32 v82, v82, v124, vcc
	v_pk_mul_f32 v[82:83], v[130:131], v[82:83]
	v_lshlrev_b32_e32 v124, 16, v78
	v_cvt_pk_bf16_f32 v107, v82, v83
	v_mad_i64_i32 v[82:83], s[12:13], v0, s2, v[144:145]
	global_store_dwordx4 v[82:83], v[104:107], off
	v_pk_fma_f32 v[82:83], v[28:29], v[102:103], v[60:61]
	v_pk_fma_f32 v[102:103], v[32:33], v[120:121], v[64:65]
	v_lshlrev_b32_e32 v104, 16, v81
	v_and_b32_e32 v105, 0xffff0000, v81
	v_lshlrev_b32_e32 v120, 16, v80
	v_and_b32_e32 v121, 0xffff0000, v80
	s_waitcnt vmcnt(8)
; __device__ __forceinline__ unsigned cvt_pk_bf16(float lo, float hi) { f32x2 v = {lo, hi}; bf16x2_t b = __builtin_convertvector(v, bf16x2_t); return __builtin_bit_cast(unsigned, b); }
; __device__ __forceinline__ void unpack8(const u32x4& r, float (&v)[8]) { v[0] = bf_lo(r.x); v[1] = bf_hi(r.x); v[2] = bf_lo(r.y); v[3] = bf_hi(r.y); v[4] = bf_lo(r.z); v[5] = bf_hi(r.z); v[6] = bf_lo(r.w); v[7] = bf_hi(r.w); }
; __device__ __forceinline__ f32x2 gelu_pk(f32x2 v) {
;     const f32x2 av = __builtin_elementwise_abs(v), d = av * 0.2316418882f + 1.0f;
;     f32x2 t; t.x = __builtin_amdgcn_rcpf(d.x); t.y = __builtin_amdgcn_rcpf(d.y);
;     f32x2 q = t * 0.5307027145f + (-0.7265760135f); q = q * t + 0.7107068705f; q = q * t + (-0.142248368f); q = q * t + 0.127414796f; q = q * t;
;     const f32x2 s = (v * v) * (-0.72134752044f);
;     f32x2 e; e.x = __builtin_amdgcn_exp2f(s.x); e.y = __builtin_amdgcn_exp2f(s.y);
;     const f32x2 m = v * (q * e), r = v - m;
;     f32x2 o; o.x = v.x < 0.f ? m.x : r.x; o.y = v.y < 0.f ? m.y : r.y; return o;
; }
; __device__ __forceinline__ void conv_phase(KP kp, int l, int a0t, int na) {
;     ...
;             for (int k = 0; k < 3; ++k) { float xa[8], xb[8]; unpack8(ra[i + k], xa); unpack8(rb[i + k], xb);
; #pragma unroll
;                 for (int e = 0; e < 8; ++e) { va[e] += wa[k][e] * xa[e]; vb[e] += wb[k][e] * xb[e]; } }
;             u32x4 o; { f32x2 gg;
;                 gg = gelu_pk((f32x2){va[0], va[1]}); o.x = cvt_pk_bf16(gg.x * vb[0], gg.y * vb[1]); gg = gelu_pk((f32x2){va[2], va[3]}); o.y = cvt_pk_bf16(gg.x * vb[2], gg.y * vb[3]);
;                 gg = gelu_pk((f32x2){va[4], va[5]}); o.z = cvt_pk_bf16(gg.x * vb[4], gg.y * vb[5]); gg = gelu_pk((f32x2){va[6], va[7]}); o.w = cvt_pk_bf16(gg.x * vb[6], gg.y * vb[7]); }
;             *(u32x4*)(ACT + (size_t)(row0 + i) * FF + j) = o;
	v_lshlrev_b32_e32 v80, 16, v76
	v_and_b32_e32 v81, 0xffff0000, v76
	v_lshlrev_b32_e32 v106, 16, v77
	v_and_b32_e32 v107, 0xffff0000, v77
	v_pk_fma_f32 v[76:77], v[50:51], v[120:121], v[100:101]
	v_pk_fma_f32 v[100:101], v[54:55], v[80:81], v[118:119]
	v_lshlrev_b32_e32 v118, 16, v79
	v_and_b32_e32 v119, 0xffff0000, v79
	v_pk_fma_f32 v[78:79], v[18:19], v[124:125], v[96:97]
	v_pk_fma_f32 v[98:99], v[20:21], v[118:119], v[98:99]
	v_and_b32_e32 v97, 0x7fffffff, v79
	v_and_b32_e32 v96, 0x7fffffff, v78
	v_pk_fma_f32 v[96:97], v[96:97], s[14:15], 1.0 op_sel_hi:[1,0,0]
	v_pk_fma_f32 v[112:113], v[6:7], v[112:113], v[42:43]
	v_rcp_f32_e32 v96, v96
	v_rcp_f32_e32 v97, v97
	v_and_b32_e32 v129, 0x7fffffff, v99
	v_and_b32_e32 v128, 0x7fffffff, v98
	v_pk_fma_f32 v[112:113], v[22:23], v[86:87], v[112:113]
	v_lshlrev_b32_e32 v126, 16, v74
	v_and_b32_e32 v127, 0xffff0000, v74
	v_pk_fma_f32 v[128:129], v[128:129], s[14:15], 1.0 op_sel_hi:[1,0,0]
	v_lshlrev_b32_e32 v122, 16, v75
	v_and_b32_e32 v123, 0xffff0000, v75
	v_pk_fma_f32 v[74:75], v[14:15], v[126:127], v[112:113]
	v_pk_fma_f32 v[112:113], v[96:97], s[38:39], v[114:115] op_sel_hi:[1,0,0]
	v_rcp_f32_e32 v128, v128
	v_rcp_f32_e32 v129, v129
	v_pk_fma_f32 v[112:113], v[96:97], v[112:113], s[10:11] op_sel_hi:[1,1,0]
	v_and_b32_e32 v131, 0x7fffffff, v77
	v_pk_fma_f32 v[112:113], v[96:97], v[112:113], s[56:57] op_sel_hi:[1,1,0]
	v_and_b32_e32 v130, 0x7fffffff, v76
	v_pk_fma_f32 v[112:113], v[96:97], v[112:113], s[64:65] op_sel_hi:[1,1,0]
	v_pk_fma_f32 v[130:131], v[130:131], s[14:15], 1.0 op_sel_hi:[1,0,0]
	v_pk_mul_f32 v[132:133], v[78:79], v[78:79]
	v_pk_mul_f32 v[96:97], v[96:97], v[112:113]
	v_pk_fma_f32 v[112:113], v[128:129], s[38:39], v[114:115] op_sel_hi:[1,0,0]
	v_rcp_f32_e32 v130, v130
	v_rcp_f32_e32 v131, v131
	v_pk_mul_f32 v[132:133], v[132:133], s[18:19] op_sel_hi:[1,0]
	v_pk_fma_f32 v[112:113], v[128:129], v[112:113], s[10:11] op_sel_hi:[1,1,0]
	v_exp_f32_e32 v132, v132
	v_exp_f32_e32 v133, v133
	v_pk_fma_f32 v[112:113], v[128:129], v[112:113], s[56:57] op_sel_hi:[1,1,0]
	v_cmp_gt_f32_e32 vcc, 0, v79
	v_pk_fma_f32 v[112:113], v[128:129], v[112:113], s[64:65] op_sel_hi:[1,1,0]
	v_pk_mul_f32 v[96:97], v[132:133], v[96:97]
	v_pk_mul_f32 v[112:113], v[128:129], v[112:113]
	v_pk_fma_f32 v[128:129], v[130:131], s[38:39], v[114:115] op_sel_hi:[1,0,0]
	v_pk_mul_f32 v[132:133], v[98:99], v[98:99]
	v_pk_fma_f32 v[128:129], v[130:131], v[128:129], s[10:11] op_sel_hi:[1,1,0]
	v_pk_mul_f32 v[132:133], v[132:133], s[18:19] op_sel_hi:[1,0]
	v_pk_fma_f32 v[128:129], v[130:131], v[128:129], s[56:57] op_sel_hi:[1,1,0]
	v_exp_f32_e32 v132, v132
	v_pk_fma_f32 v[128:129], v[130:131], v[128:129], s[64:65] op_sel_hi:[1,1,0]
	v_exp_f32_e32 v133, v133
	v_pk_mul_f32 v[128:129], v[130:131], v[128:129]
	v_pk_mul_f32 v[130:131], v[78:79], v[96:97]
	v_pk_fma_f32 v[96:97], v[78:79], v[96:97], v[78:79] neg_lo:[1,0,0] neg_hi:[1,0,0]
	v_pk_fma_f32 v[2:3], v[2:3], v[84:85], v[38:39]
	v_cndmask_b32_e32 v79, v97, v131, vcc
	v_cmp_gt_f32_e32 vcc, 0, v78
	v_pk_fma_f32 v[2:3], v[10:11], v[124:125], v[2:3]
	s_waitcnt vmcnt(6)
	v_lshlrev_b32_e32 v10, 16, v70
	v_and_b32_e32 v11, 0xffff0000, v70
	v_cndmask_b32_e32 v78, v96, v130, vcc
	v_pk_fma_f32 v[2:3], v[18:19], v[10:11], v[2:3]
	v_pk_mul_f32 v[74:75], v[74:75], v[78:79]
	v_pk_mul_f32 v[78:79], v[132:133], v[112:113]
	v_pk_mul_f32 v[112:113], v[76:77], v[76:77]
	v_and_b32_e32 v11, 0x7fffffff, v3
	v_and_b32_e32 v10, 0x7fffffff, v2
	v_pk_mul_f32 v[112:113], v[112:113], s[18:19] op_sel_hi:[1,0]
	v_pk_fma_f32 v[4:5], v[4:5], v[88:89], v[40:41]
	v_pk_fma_f32 v[10:11], v[10:11], s[14:15], 1.0 op_sel_hi:[1,0,0]
	v_pk_fma_f32 v[82:83], v[36:37], v[92:93], v[82:83]
	v_pk_fma_f32 v[116:117], v[8:9], v[116:117], v[44:45]
	v_pk_mul_f32 v[96:97], v[98:99], v[78:79]
	v_pk_fma_f32 v[78:79], v[98:99], v[78:79], v[98:99] neg_lo:[1,0,0] neg_hi:[1,0,0]
	v_cmp_gt_f32_e32 vcc, 0, v99
	v_exp_f32_e32 v112, v112
	v_exp_f32_e32 v113, v113
	v_pk_fma_f32 v[4:5], v[12:13], v[118:119], v[4:5]
	v_lshlrev_b32_e32 v12, 16, v71
	v_and_b32_e32 v13, 0xffff0000, v71
	v_pk_fma_f32 v[6:7], v[6:7], v[86:87], v[42:43]
	v_rcp_f32_e32 v10, v10
	v_rcp_f32_e32 v11, v11
	v_pk_fma_f32 v[82:83], v[52:53], v[104:105], v[82:83]
	v_pk_fma_f32 v[116:117], v[24:25], v[94:95], v[116:117]
	v_cndmask_b32_e32 v79, v79, v97, vcc
	v_cmp_gt_f32_e32 vcc, 0, v98
	v_pk_fma_f32 v[4:5], v[20:21], v[12:13], v[4:5]
	v_pk_fma_f32 v[6:7], v[22:23], v[126:127], v[6:7]
	v_lshlrev_b32_e32 v12, 16, v66
	v_and_b32_e32 v13, 0xffff0000, v66
	v_pk_fma_f32 v[116:117], v[16:17], v[122:123], v[116:117]
	v_cndmask_b32_e32 v78, v78, v96, vcc
	v_and_b32_e32 v99, 0x7fffffff, v83
	v_and_b32_e32 v98, 0x7fffffff, v82
	v_pk_fma_f32 v[6:7], v[14:15], v[12:13], v[6:7]
	v_and_b32_e32 v15, 0x7fffffff, v5
	v_and_b32_e32 v14, 0x7fffffff, v4
	v_pk_mul_f32 v[78:79], v[116:117], v[78:79]
	v_pk_fma_f32 v[98:99], v[98:99], s[14:15], 1.0 op_sel_hi:[1,0,0]
	v_pk_fma_f32 v[26:27], v[26:27], v[90:91], v[58:59]
	v_pk_fma_f32 v[14:15], v[14:15], s[14:15], 1.0 op_sel_hi:[1,0,0]
	v_cvt_pk_bf16_f32 v74, v74, v75
	v_cvt_pk_bf16_f32 v75, v78, v79
	v_pk_mul_f32 v[78:79], v[112:113], v[128:129]
	v_rcp_f32_e32 v98, v98
	v_rcp_f32_e32 v99, v99
	v_pk_fma_f32 v[26:27], v[34:35], v[120:121], v[26:27]
	v_lshlrev_b32_e32 v34, 16, v72
	v_and_b32_e32 v35, 0xffff0000, v72
	v_pk_fma_f32 v[8:9], v[8:9], v[94:95], v[44:45]
	v_pk_fma_f32 v[12:13], v[10:11], s[38:39], v[114:115] op_sel_hi:[1,0,0]
	v_rcp_f32_e32 v14, v14
	v_rcp_f32_e32 v15, v15
	v_pk_mul_f32 v[96:97], v[76:77], v[78:79]
	v_pk_fma_f32 v[78:79], v[76:77], v[78:79], v[76:77] neg_lo:[1,0,0] neg_hi:[1,0,0]
	v_cmp_gt_f32_e32 vcc, 0, v77
; __device__ __forceinline__ unsigned cvt_pk_bf16(float lo, float hi) { f32x2 v = {lo, hi}; bf16x2_t b = __builtin_convertvector(v, bf16x2_t); return __builtin_bit_cast(unsigned, b); }
; __device__ __forceinline__ void unpack8(const u32x4& r, float (&v)[8]) { v[0] = bf_lo(r.x); v[1] = bf_hi(r.x); v[2] = bf_lo(r.y); v[3] = bf_hi(r.y); v[4] = bf_lo(r.z); v[5] = bf_hi(r.z); v[6] = bf_lo(r.w); v[7] = bf_hi(r.w); }
; __device__ __forceinline__ void conv_phase(KP kp, int l, int a0t, int na) {
;     ...
;     for (int idx = blockIdx.x * 512 + tid_; idx < total; idx += NT) {
;     ...
;             for (int k = 0; k < 3; ++k) { float xa[8], xb[8]; unpack8(ra[i + k], xa); unpack8(rb[i + k], xb);
; #pragma unroll
;                 for (int e = 0; e < 8; ++e) { va[e] += wa[k][e] * xa[e]; vb[e] += wb[k][e] * xb[e]; } }
;             u32x4 o; { f32x2 gg;
;                 gg = gelu_pk((f32x2){va[0], va[1]}); o.x = cvt_pk_bf16(gg.x * vb[0], gg.y * vb[1]); gg = gelu_pk((f32x2){va[2], va[3]}); o.y = cvt_pk_bf16(gg.x * vb[2], gg.y * vb[3]);
;                 gg = gelu_pk((f32x2){va[4], va[5]}); o.z = cvt_pk_bf16(gg.x * vb[4], gg.y * vb[5]); gg = gelu_pk((f32x2){va[6], va[7]}); o.w = cvt_pk_bf16(gg.x * vb[6], gg.y * vb[7]); }
;             *(u32x4*)(ACT + (size_t)(row0 + i) * FF + j) = o;
	v_pk_fma_f32 v[26:27], v[50:51], v[34:35], v[26:27]
	v_pk_fma_f32 v[8:9], v[24:25], v[122:123], v[8:9]
	v_lshlrev_b32_e32 v24, 16, v67
	v_and_b32_e32 v25, 0xffff0000, v67
	v_pk_fma_f32 v[12:13], v[10:11], v[12:13], s[10:11] op_sel_hi:[1,1,0]
	v_cndmask_b32_e32 v77, v79, v97, vcc
	v_cmp_gt_f32_e32 vcc, 0, v76
	v_pk_fma_f32 v[8:9], v[16:17], v[24:25], v[8:9]
	v_pk_fma_f32 v[12:13], v[10:11], v[12:13], s[56:57] op_sel_hi:[1,1,0]
	v_and_b32_e32 v17, 0x7fffffff, v27
	v_and_b32_e32 v16, 0x7fffffff, v26
	v_cndmask_b32_e32 v76, v78, v96, vcc
	v_pk_mul_f32 v[96:97], v[82:83], v[82:83]
	v_pk_fma_f32 v[12:13], v[10:11], v[12:13], s[64:65] op_sel_hi:[1,1,0]
	v_pk_fma_f32 v[16:17], v[16:17], s[14:15], 1.0 op_sel_hi:[1,0,0]
	v_pk_mul_f32 v[18:19], v[2:3], v[2:3]
	v_pk_fma_f32 v[78:79], v[98:99], s[38:39], v[114:115] op_sel_hi:[1,0,0]
	v_pk_mul_f32 v[96:97], v[96:97], s[18:19] op_sel_hi:[1,0]
	v_pk_mul_f32 v[10:11], v[10:11], v[12:13]
	v_pk_fma_f32 v[12:13], v[14:15], s[38:39], v[114:115] op_sel_hi:[1,0,0]
	v_rcp_f32_e32 v16, v16
	v_rcp_f32_e32 v17, v17
	v_pk_mul_f32 v[18:19], v[18:19], s[18:19] op_sel_hi:[1,0]
	v_pk_fma_f32 v[78:79], v[98:99], v[78:79], s[10:11] op_sel_hi:[1,1,0]
	v_exp_f32_e32 v96, v96
	v_exp_f32_e32 v97, v97
	v_pk_fma_f32 v[12:13], v[14:15], v[12:13], s[10:11] op_sel_hi:[1,1,0]
	v_exp_f32_e32 v18, v18
	v_exp_f32_e32 v19, v19
	v_pk_fma_f32 v[78:79], v[98:99], v[78:79], s[56:57] op_sel_hi:[1,1,0]
	v_pk_fma_f32 v[12:13], v[14:15], v[12:13], s[56:57] op_sel_hi:[1,1,0]
	v_pk_fma_f32 v[78:79], v[98:99], v[78:79], s[64:65] op_sel_hi:[1,1,0]
	v_pk_fma_f32 v[12:13], v[14:15], v[12:13], s[64:65] op_sel_hi:[1,1,0]
	v_pk_mul_f32 v[78:79], v[98:99], v[78:79]
	v_pk_mul_f32 v[12:13], v[14:15], v[12:13]
	v_pk_fma_f32 v[14:15], v[16:17], s[38:39], v[114:115] op_sel_hi:[1,0,0]
	v_pk_mul_f32 v[78:79], v[96:97], v[78:79]
	v_pk_fma_f32 v[14:15], v[16:17], v[14:15], s[10:11] op_sel_hi:[1,1,0]
	v_pk_mul_f32 v[10:11], v[18:19], v[10:11]
	v_pk_mul_f32 v[18:19], v[4:5], v[4:5]
	v_pk_mul_f32 v[96:97], v[82:83], v[78:79]
	v_pk_fma_f32 v[78:79], v[82:83], v[78:79], v[82:83] neg_lo:[1,0,0] neg_hi:[1,0,0]
	v_cmp_gt_f32_e32 vcc, 0, v83
	v_pk_fma_f32 v[14:15], v[16:17], v[14:15], s[56:57] op_sel_hi:[1,1,0]
	v_pk_mul_f32 v[18:19], v[18:19], s[18:19] op_sel_hi:[1,0]
	v_cndmask_b32_e32 v79, v79, v97, vcc
	v_cmp_gt_f32_e32 vcc, 0, v82
	v_pk_fma_f32 v[14:15], v[16:17], v[14:15], s[64:65] op_sel_hi:[1,1,0]
	v_exp_f32_e32 v18, v18
	v_exp_f32_e32 v19, v19
	v_cndmask_b32_e32 v78, v78, v96, vcc
	v_pk_mul_f32 v[14:15], v[16:17], v[14:15]
	v_pk_mul_f32 v[16:17], v[2:3], v[10:11]
	v_pk_fma_f32 v[10:11], v[2:3], v[10:11], v[2:3] neg_lo:[1,0,0] neg_hi:[1,0,0]
	v_cmp_gt_f32_e32 vcc, 0, v3
	v_pk_fma_f32 v[28:29], v[28:29], v[92:93], v[60:61]
	v_pk_fma_f32 v[102:103], v[48:49], v[110:111], v[102:103]
	v_cndmask_b32_e32 v3, v11, v17, vcc
	v_cmp_gt_f32_e32 vcc, 0, v2
	v_pk_fma_f32 v[28:29], v[36:37], v[104:105], v[28:29]
	v_lshlrev_b32_e32 v36, 16, v73
	v_cndmask_b32_e32 v2, v10, v16, vcc
	v_pk_mul_f32 v[2:3], v[6:7], v[2:3]
	v_pk_mul_f32 v[6:7], v[18:19], v[12:13]
	v_cmp_gt_f32_e32 vcc, 0, v5
	v_pk_mul_f32 v[10:11], v[4:5], v[6:7]
	v_pk_fma_f32 v[6:7], v[4:5], v[6:7], v[4:5] neg_lo:[1,0,0] neg_hi:[1,0,0]
	v_pk_mul_f32 v[12:13], v[26:27], v[26:27]
	v_and_b32_e32 v37, 0xffff0000, v73
	v_cndmask_b32_e32 v5, v7, v11, vcc
	v_pk_mul_f32 v[12:13], v[12:13], s[18:19] op_sel_hi:[1,0]
	v_cmp_gt_f32_e32 vcc, 0, v4
	v_pk_fma_f32 v[28:29], v[52:53], v[36:37], v[28:29]
	v_exp_f32_e32 v12, v12
	v_exp_f32_e32 v13, v13
	v_cndmask_b32_e32 v4, v6, v10, vcc
	v_pk_mul_f32 v[4:5], v[8:9], v[4:5]
	v_and_b32_e32 v9, 0x7fffffff, v29
	v_and_b32_e32 v8, 0x7fffffff, v28
	v_pk_fma_f32 v[8:9], v[8:9], s[14:15], 1.0 op_sel_hi:[1,0,0]
	v_cvt_pk_bf16_f32 v2, v2, v3
	v_rcp_f32_e32 v8, v8
	v_rcp_f32_e32 v9, v9
	v_cvt_pk_bf16_f32 v3, v4, v5
	v_pk_mul_f32 v[4:5], v[12:13], v[14:15]
	v_cmp_gt_f32_e32 vcc, 0, v27
	v_pk_mul_f32 v[6:7], v[26:27], v[4:5]
	v_pk_fma_f32 v[4:5], v[26:27], v[4:5], v[26:27] neg_lo:[1,0,0] neg_hi:[1,0,0]
	v_pk_mul_f32 v[10:11], v[28:29], v[28:29]
	v_cndmask_b32_e32 v5, v5, v7, vcc
	v_cmp_gt_f32_e32 vcc, 0, v26
	v_pk_mul_f32 v[10:11], v[10:11], s[18:19] op_sel_hi:[1,0]
	v_pk_fma_f32 v[32:33], v[32:33], v[110:111], v[64:65]
	v_cndmask_b32_e32 v4, v4, v6, vcc
	v_pk_fma_f32 v[6:7], v[8:9], s[38:39], v[114:115] op_sel_hi:[1,0,0]
	v_exp_f32_e32 v10, v10
	v_pk_fma_f32 v[6:7], v[8:9], v[6:7], s[10:11] op_sel_hi:[1,1,0]
	v_exp_f32_e32 v11, v11
	v_pk_fma_f32 v[6:7], v[8:9], v[6:7], s[56:57] op_sel_hi:[1,1,0]
	v_pk_fma_f32 v[30:31], v[30:31], v[108:109], v[62:63]
	v_pk_fma_f32 v[6:7], v[8:9], v[6:7], s[64:65] op_sel_hi:[1,1,0]
	v_cmp_gt_f32_e32 vcc, 0, v29
	v_pk_mul_f32 v[6:7], v[8:9], v[6:7]
	v_pk_fma_f32 v[102:103], v[56:57], v[106:107], v[102:103]
	v_pk_mul_f32 v[6:7], v[10:11], v[6:7]
	v_pk_fma_f32 v[32:33], v[48:49], v[106:107], v[32:33]
	v_pk_mul_f32 v[8:9], v[28:29], v[6:7]
	v_pk_fma_f32 v[6:7], v[28:29], v[6:7], v[28:29] neg_lo:[1,0,0] neg_hi:[1,0,0]
	v_lshlrev_b32_e32 v48, 16, v69
	v_and_b32_e32 v49, 0xffff0000, v69
	v_pk_fma_f32 v[30:31], v[46:47], v[80:81], v[30:31]
	v_lshlrev_b32_e32 v36, 16, v68
	v_and_b32_e32 v37, 0xffff0000, v68
	v_cndmask_b32_e32 v7, v7, v9, vcc
	v_cmp_gt_f32_e32 vcc, 0, v28
	v_pk_mul_f32 v[76:77], v[100:101], v[76:77]
	v_pk_mul_f32 v[78:79], v[102:103], v[78:79]
	v_or_b32_e32 v0, 6, v164
	v_pk_fma_f32 v[32:33], v[56:57], v[48:49], v[32:33]
	v_pk_fma_f32 v[30:31], v[54:55], v[36:37], v[30:31]
	v_cndmask_b32_e32 v6, v6, v8, vcc
	v_cvt_pk_bf16_f32 v76, v76, v77
	v_cvt_pk_bf16_f32 v77, v78, v79
	v_mad_i64_i32 v[78:79], s[12:13], v0, s2, v[144:145]
	v_pk_mul_f32 v[4:5], v[30:31], v[4:5]
	v_pk_mul_f32 v[6:7], v[32:33], v[6:7]
	v_or_b32_e32 v0, 7, v164
	v_cvt_pk_bf16_f32 v4, v4, v5
	v_cvt_pk_bf16_f32 v5, v6, v7
	v_mad_i64_i32 v[6:7], s[12:13], v0, s2, v[144:145]
	s_mov_b32 s2, 0x4ffff
	v_cmp_lt_i32_e32 vcc, s2, v143
	s_or_b64 s[62:63], vcc, s[62:63]
	global_store_dwordx4 v[78:79], v[74:77], off
	global_store_dwordx4 v[6:7], v[2:5], off
	s_andn2_b64 exec, exec, s[62:63]
	s_cbranch_execz .LBB0_38
